# in-proj epilogue: second-half column constants loaded with the first half's (v236-243), no wait behind the first half's stores
# speedup vs baseline: 1.0210x; 1.0043x over previous
;     template <int KIND>
;     __device__ __forceinline__ void run(const f32x4 (&acc)[2][2][4][2], const Unit& u, int wr, int wc, int fr, int fq) const {
;         const int row0 = u.pm * BM + wr * 64 + fr, col0 = u.pn * BM + wc * 32 + 8 * fq;
;         const float sa_lo = sa[u.pm * BM + wr * 64 + fr + 16 * fq], sa_hi = sa[u.pm * BM + HALF + wr * 64 + fr + 16 * fq];
; #pragma unroll
;         for (int bj = 0; bj < 2; ++bj) {
;             f32x2_t sc2[4], aux2[4];
; #pragma unroll
;             for (int j = 0; j < 4; ++j) {
;                 const float k0 = (KIND == 4) ? (0.125f * LOG2E / 127.0f) : (1.0f / 127.0f);
;                 sc2[j] = (f32x2_t){wmax[col0 + bj * HALF + 2 * j] * k0, wmax[col0 + bj * HALF + 2 * j + 1] * k0};
;                 if (KIND == 1) aux2[j] = (f32x2_t){lb[col0 - C_HG + bj * HALF + 2 * j], lb[col0 - C_HG + bj * HALF + 2 * j + 1]};
;                 else if (KIND == 3) aux2[j] = (f32x2_t){gain[col0 - C_HGATE + bj * HALF + 2 * j], gain[col0 - C_HGATE + bj * HALF + 2 * j + 1]};
;                 else aux2[j] = (f32x2_t){0.f, 0.f};
;             }
; #pragma unroll
;             for (int ai = 0; ai < 2; ++ai)
; #pragma unroll
;                 for (int m = 0; m < 4; ++m) { const int row = row0 + ai * HALF + m * 16; const float a = __shfl(ai ? sa_hi : sa_lo, 16 * m + fr);
;                     const f32x4 f0 = __builtin_convertvector(__builtin_bit_cast(i32x4, acc[ai][bj][m][0]), f32x4), f1 = __builtin_convertvector(__builtin_bit_cast(i32x4, acc[ai][bj][m][1]), f32x4);
;                     f32x2_t v[4] = {(f32x2_t){f0[0], f0[1]}, (f32x2_t){f0[2], f0[3]}, (f32x2_t){f1[0], f1[1]}, (f32x2_t){f1[2], f1[3]}};
; #pragma unroll
;                     for (int j = 0; j < 4; ++j) {
;                         v[j] = v[j] * (sc2[j] * (f32x2_t){a, a});
;                         if (KIND == 0 || KIND == 1 || KIND == 3) {
;                             const f32x2_t e = v[j] * (f32x2_t){-LOG2E, -LOG2E};
;                             const f32x2_t dn = (f32x2_t){__builtin_amdgcn_exp2f(e[0]), __builtin_amdgcn_exp2f(e[1])} + (f32x2_t){1.0f, 1.0f};
;                             const f32x2_t sg = (f32x2_t){fast_rcp(dn[0]), fast_rcp(dn[1])};
;                             if (KIND == 0) v[j] = v[j] * sg;
;                             else if (KIND == 3) v[j] = (v[j] * sg) * aux2[j];
.LBB0_206:
	s_mov_b64 s[0:1], -1
	s_cmp_gt_u32 s2, 1
	v_lshl_or_b32 v146, s2, 8, v216
	s_cbranch_scc0 .LBB0_212
	s_lshl_b32 s0, s90, 8
	v_add_u32_e32 v175, s0, v212
	v_or_b32_e32 v132, v175, v214
	v_ashrrev_i32_e32 v133, 31, v132
	v_add_u32_e32 v134, s0, v215
	v_ashrrev_i32_e32 v147, 31, v146
	v_lshl_add_u64 v[132:133], v[132:133], 2, s[46:47]
	v_ashrrev_i32_e32 v135, 31, v134
	v_lshl_add_u64 v[148:149], v[146:147], 2, s[48:49]
	v_lshl_add_u64 v[134:135], v[134:135], 2, s[46:47]
	global_load_dword v209, v[132:133], off
	global_load_dword v208, v[134:135], off
	global_load_dwordx2 v[154:155], v[148:149], off
	s_ashr_i32 s16, s2, 1
	s_mov_b64 s[10:11], -1
	s_mov_b64 s[0:1], 0
	s_cmp_lt_i32 s16, 3
	s_mov_b64 s[8:9], 0
	s_cbranch_scc1 .LBB0_220
	s_cmp_gt_i32 s16, 3
	s_cbranch_scc0 .LBB0_217
	s_cmp_eq_u32 s16, 4
	s_mov_b64 s[8:9], -1
	s_cbranch_scc0 .LBB0_211
	global_load_dwordx2 v[150:151], v[148:149], off offset:24
	global_load_dwordx4 v[134:137], v[148:149], off offset:8
	global_load_dwordx4 v[236:239], v[148:149], off offset:528
	global_load_dwordx4 v[240:243], v[148:149], off offset:512
	s_mov_b32 s6, 0x3aba1e78
	v_cvt_f32_i32_e32 v157, v129
	v_cvt_f32_i32_e32 v156, v128
	v_cvt_f32_i32_e32 v153, v131
	v_cvt_f32_i32_e32 v152, v130
	s_waitcnt vmcnt(0)
	v_pk_mul_f32 v[132:133], v[154:155], s[6:7] op_sel_hi:[1,0]
	v_cvt_f32_i32_e32 v161, v125
	v_cvt_f32_i32_e32 v160, v124
	v_cvt_f32_i32_e32 v159, v127
	v_cvt_f32_i32_e32 v158, v126
	v_lshlrev_b64 v[164:165], 1, v[146:147]
	v_cvt_f32_i32_e32 v169, v117
	v_cvt_f32_i32_e32 v168, v116
	v_cvt_f32_i32_e32 v167, v119
	v_cvt_f32_i32_e32 v166, v118
	v_cvt_f32_i32_e32 v173, v109
	v_cvt_f32_i32_e32 v172, v108
	v_cvt_f32_i32_e32 v179, v101
	v_cvt_f32_i32_e32 v178, v100
	v_cvt_f32_i32_e32 v183, v93
	v_cvt_f32_i32_e32 v182, v92
	v_cvt_f32_i32_e32 v187, v85
	v_cvt_f32_i32_e32 v186, v84
	s_mov_b64 s[8:9], 0
	v_pk_mul_f32 v[138:139], v[134:135], s[6:7] op_sel_hi:[1,0]
	v_pk_mul_f32 v[134:135], v[150:151], s[6:7] op_sel_hi:[1,0]
	v_lshlrev_b32_e32 v150, 2, v233
	ds_bpermute_b32 v66, v150, v209
	v_pk_mul_f32 v[136:137], v[136:137], s[6:7] op_sel_hi:[1,0]
	v_or_b32_e32 v151, 16, v175
	ds_bpermute_b32 v174, v150, v208 offset:128
	s_waitcnt lgkmcnt(1)
	v_pk_mul_f32 v[162:163], v[132:133], v[66:67] op_sel_hi:[1,0]
	s_nop 0
	v_pk_mul_f32 v[156:157], v[156:157], v[162:163]
	v_pk_mul_f32 v[162:163], v[138:139], v[66:67] op_sel_hi:[1,0]
	s_waitcnt lgkmcnt(0)
	v_pk_mul_f32 v[190:191], v[132:133], v[174:175] op_sel_hi:[1,0]
	v_pk_mul_f32 v[152:153], v[152:153], v[162:163]
	v_pk_mul_f32 v[162:163], v[136:137], v[66:67] op_sel_hi:[1,0]
	s_nop 0
	v_pk_mul_f32 v[160:161], v[160:161], v[162:163]
	v_pk_mul_f32 v[162:163], v[134:135], v[66:67] op_sel_hi:[1,0]
	v_cvt_pk_bf16_f32 v160, v160, v161
	v_pk_mul_f32 v[162:163], v[158:159], v[162:163]
	v_cvt_pk_bf16_f32 v159, v152, v153
	v_cvt_pk_bf16_f32 v161, v162, v163
	v_mov_b64_e32 v[162:163], s[14:15]
	v_mad_i64_i32 v[152:153], s[2:3], v175, s81, v[162:163]
	v_cvt_pk_bf16_f32 v158, v156, v157
	v_lshl_add_u64 v[156:157], v[152:153], 0, v[164:165]
	ds_bpermute_b32 v152, v150, v209 offset:64
	global_store_dwordx4 v[156:157], v[158:161], off
	s_waitcnt lgkmcnt(0)
	v_pk_mul_f32 v[170:171], v[132:133], v[152:153] op_sel_hi:[1,0]
	v_cvt_f32_i32_e32 v161, v121
	v_cvt_f32_i32_e32 v160, v120
	v_cvt_f32_i32_e32 v159, v123
	v_cvt_f32_i32_e32 v158, v122
	v_pk_mul_f32 v[160:161], v[160:161], v[170:171]
	v_pk_mul_f32 v[170:171], v[138:139], v[152:153] op_sel_hi:[1,0]
	s_nop 0
	v_pk_mul_f32 v[158:159], v[158:159], v[170:171]
	v_pk_mul_f32 v[170:171], v[136:137], v[152:153] op_sel_hi:[1,0]
	s_nop 0
	v_pk_mul_f32 v[168:169], v[168:169], v[170:171]
	v_pk_mul_f32 v[170:171], v[134:135], v[152:153] op_sel_hi:[1,0]
	v_cvt_pk_bf16_f32 v168, v168, v169
	v_pk_mul_f32 v[170:171], v[166:167], v[170:171]
	v_cvt_pk_bf16_f32 v167, v158, v159
	v_mad_i64_i32 v[158:159], s[2:3], v151, s81, v[162:163]
	v_cvt_pk_bf16_f32 v166, v160, v161
	v_lshl_add_u64 v[160:161], v[158:159], 0, v[164:165]
	ds_bpermute_b32 v158, v150, v209 offset:128
	v_cvt_pk_bf16_f32 v169, v170, v171
	global_store_dwordx4 v[160:161], v[166:169], off
	v_cvt_f32_i32_e32 v171, v111
	v_cvt_f32_i32_e32 v170, v110
	v_cvt_f32_i32_e32 v169, v113
	v_cvt_f32_i32_e32 v168, v112
	v_cvt_f32_i32_e32 v167, v115
	v_cvt_f32_i32_e32 v166, v114
	s_waitcnt lgkmcnt(0)
	v_pk_mul_f32 v[176:177], v[132:133], v[158:159] op_sel_hi:[1,0]
	v_or_b32_e32 v151, 32, v175
	v_pk_mul_f32 v[168:169], v[168:169], v[176:177]
	v_pk_mul_f32 v[176:177], v[138:139], v[158:159] op_sel_hi:[1,0]
	v_cvt_pk_bf16_f32 v168, v168, v169
	v_pk_mul_f32 v[166:167], v[166:167], v[176:177]
	v_pk_mul_f32 v[176:177], v[136:137], v[158:159] op_sel_hi:[1,0]
	v_cvt_pk_bf16_f32 v169, v166, v167
	v_pk_mul_f32 v[172:173], v[172:173], v[176:177]
	v_pk_mul_f32 v[176:177], v[134:135], v[158:159] op_sel_hi:[1,0]
	v_mad_i64_i32 v[166:167], s[2:3], v151, s81, v[162:163]
	v_pk_mul_f32 v[176:177], v[170:171], v[176:177]
	v_cvt_pk_bf16_f32 v170, v172, v173
	v_cvt_pk_bf16_f32 v171, v176, v177
	v_lshl_add_u64 v[166:167], v[166:167], 0, v[164:165]
	global_store_dwordx4 v[166:167], v[168:171], off
	ds_bpermute_b32 v168, v150, v209 offset:192
	v_cvt_f32_i32_e32 v173, v105
	v_cvt_f32_i32_e32 v172, v104
	v_cvt_f32_i32_e32 v171, v107
	v_cvt_f32_i32_e32 v170, v106
	v_cvt_f32_i32_e32 v177, v103
	v_cvt_f32_i32_e32 v176, v102
	s_waitcnt lgkmcnt(0)
;     template <int KIND>
;     __device__ __forceinline__ void run(const f32x4 (&acc)[2][2][4][2], const Unit& u, int wr, int wc, int fr, int fq) const {
;         const int row0 = u.pm * BM + wr * 64 + fr, col0 = u.pn * BM + wc * 32 + 8 * fq;
;         const float sa_lo = sa[u.pm * BM + wr * 64 + fr + 16 * fq], sa_hi = sa[u.pm * BM + HALF + wr * 64 + fr + 16 * fq];
; #pragma unroll
;         for (int bj = 0; bj < 2; ++bj) {
;             f32x2_t sc2[4], aux2[4];
; #pragma unroll
;             for (int j = 0; j < 4; ++j) {
;                 const float k0 = (KIND == 4) ? (0.125f * LOG2E / 127.0f) : (1.0f / 127.0f);
;                 sc2[j] = (f32x2_t){wmax[col0 + bj * HALF + 2 * j] * k0, wmax[col0 + bj * HALF + 2 * j + 1] * k0};
;                 if (KIND == 1) aux2[j] = (f32x2_t){lb[col0 - C_HG + bj * HALF + 2 * j], lb[col0 - C_HG + bj * HALF + 2 * j + 1]};
;                 else if (KIND == 3) aux2[j] = (f32x2_t){gain[col0 - C_HGATE + bj * HALF + 2 * j], gain[col0 - C_HGATE + bj * HALF + 2 * j + 1]};
;                 else aux2[j] = (f32x2_t){0.f, 0.f};
;             }
; #pragma unroll
;             for (int ai = 0; ai < 2; ++ai)
; #pragma unroll
;                 for (int m = 0; m < 4; ++m) { const int row = row0 + ai * HALF + m * 16; const float a = __shfl(ai ? sa_hi : sa_lo, 16 * m + fr);
;                     const f32x4 f0 = __builtin_convertvector(__builtin_bit_cast(i32x4, acc[ai][bj][m][0]), f32x4), f1 = __builtin_convertvector(__builtin_bit_cast(i32x4, acc[ai][bj][m][1]), f32x4);
;                     f32x2_t v[4] = {(f32x2_t){f0[0], f0[1]}, (f32x2_t){f0[2], f0[3]}, (f32x2_t){f1[0], f1[1]}, (f32x2_t){f1[2], f1[3]}};
; #pragma unroll
;                     for (int j = 0; j < 4; ++j) {
;                         v[j] = v[j] * (sc2[j] * (f32x2_t){a, a});
;                         if (KIND == 0 || KIND == 1 || KIND == 3) {
;                             const f32x2_t e = v[j] * (f32x2_t){-LOG2E, -LOG2E};
;                             const f32x2_t dn = (f32x2_t){__builtin_amdgcn_exp2f(e[0]), __builtin_amdgcn_exp2f(e[1])} + (f32x2_t){1.0f, 1.0f};
;                             const f32x2_t sg = (f32x2_t){fast_rcp(dn[0]), fast_rcp(dn[1])};
;                             if (KIND == 0) v[j] = v[j] * sg;
;                             else if (KIND == 3) v[j] = (v[j] * sg) * aux2[j];
	v_pk_mul_f32 v[180:181], v[132:133], v[168:169] op_sel_hi:[1,0]
	v_or_b32_e32 v151, 48, v175
	v_pk_mul_f32 v[172:173], v[172:173], v[180:181]
	v_pk_mul_f32 v[180:181], v[138:139], v[168:169] op_sel_hi:[1,0]
	v_add_u32_e32 v153, 0xb0, v175
	v_pk_mul_f32 v[180:181], v[170:171], v[180:181]
	v_pk_mul_f32 v[170:171], v[136:137], v[168:169] op_sel_hi:[1,0]
	s_nop 0
	v_pk_mul_f32 v[178:179], v[178:179], v[170:171]
	v_pk_mul_f32 v[170:171], v[134:135], v[168:169] op_sel_hi:[1,0]
	s_nop 0
	v_pk_mul_f32 v[176:177], v[176:177], v[170:171]
	v_cvt_pk_bf16_f32 v170, v172, v173
	v_cvt_pk_bf16_f32 v173, v176, v177
	v_mad_i64_i32 v[176:177], s[2:3], v151, s81, v[162:163]
	v_cvt_pk_bf16_f32 v171, v180, v181
	v_cvt_pk_bf16_f32 v172, v178, v179
	v_lshl_add_u64 v[178:179], v[176:177], 0, v[164:165]
	global_store_dwordx4 v[178:179], v[170:173], off
	ds_bpermute_b32 v170, v150, v208
	v_cvt_f32_i32_e32 v177, v97
	v_cvt_f32_i32_e32 v176, v96
	v_cvt_f32_i32_e32 v173, v99
	v_cvt_f32_i32_e32 v172, v98
	v_cvt_f32_i32_e32 v181, v95
	v_cvt_f32_i32_e32 v180, v94
	s_waitcnt lgkmcnt(0)
	v_pk_mul_f32 v[184:185], v[132:133], v[170:171] op_sel_hi:[1,0]
	v_add_u32_e32 v151, 0x80, v175
	v_pk_mul_f32 v[176:177], v[176:177], v[184:185]
	v_pk_mul_f32 v[184:185], v[138:139], v[170:171] op_sel_hi:[1,0]
	s_nop 0
	v_pk_mul_f32 v[172:173], v[172:173], v[184:185]
	v_pk_mul_f32 v[184:185], v[136:137], v[170:171] op_sel_hi:[1,0]
	s_nop 0
	v_pk_mul_f32 v[184:185], v[182:183], v[184:185]
	v_pk_mul_f32 v[182:183], v[134:135], v[170:171] op_sel_hi:[1,0]
	v_cvt_pk_bf16_f32 v184, v184, v185
	v_pk_mul_f32 v[180:181], v[180:181], v[182:183]
	v_cvt_pk_bf16_f32 v183, v172, v173
	v_mad_i64_i32 v[172:173], s[2:3], v151, s81, v[162:163]
	v_cvt_pk_bf16_f32 v185, v180, v181
	v_lshl_add_u64 v[180:181], v[172:173], 0, v[164:165]
	ds_bpermute_b32 v172, v150, v208 offset:64
	v_cvt_pk_bf16_f32 v182, v176, v177
	global_store_dwordx4 v[180:181], v[182:185], off
	v_cvt_f32_i32_e32 v177, v91
	v_cvt_f32_i32_e32 v176, v90
	v_cvt_f32_i32_e32 v183, v89
	v_cvt_f32_i32_e32 v182, v88
	v_cvt_f32_i32_e32 v185, v87
	v_cvt_f32_i32_e32 v184, v86
	s_waitcnt lgkmcnt(0)
	v_pk_mul_f32 v[188:189], v[132:133], v[172:173] op_sel_hi:[1,0]
	v_add_u32_e32 v151, 0x90, v175
	v_pk_mul_f32 v[182:183], v[182:183], v[188:189]
	v_pk_mul_f32 v[188:189], v[138:139], v[172:173] op_sel_hi:[1,0]
	s_nop 0
	v_pk_mul_f32 v[176:177], v[176:177], v[188:189]
	v_pk_mul_f32 v[188:189], v[136:137], v[172:173] op_sel_hi:[1,0]
	s_nop 0
	v_pk_mul_f32 v[186:187], v[186:187], v[188:189]
	v_pk_mul_f32 v[188:189], v[134:135], v[172:173] op_sel_hi:[1,0]
	v_cvt_pk_bf16_f32 v186, v186, v187
	v_pk_mul_f32 v[188:189], v[184:185], v[188:189]
	v_cvt_pk_bf16_f32 v185, v176, v177
	v_mad_i64_i32 v[176:177], s[2:3], v151, s81, v[162:163]
	v_cvt_pk_bf16_f32 v184, v182, v183
	v_cvt_pk_bf16_f32 v187, v188, v189
	v_lshl_add_u64 v[182:183], v[176:177], 0, v[164:165]
	global_store_dwordx4 v[182:183], v[184:187], off
	v_cvt_f32_i32_e32 v177, v83
	v_cvt_f32_i32_e32 v176, v82
	v_cvt_f32_i32_e32 v185, v81
	v_cvt_f32_i32_e32 v184, v80
	v_cvt_f32_i32_e32 v189, v77
	v_cvt_f32_i32_e32 v188, v76
	v_cvt_f32_i32_e32 v187, v79
	v_cvt_f32_i32_e32 v186, v78
	v_pk_mul_f32 v[184:185], v[184:185], v[190:191]
	v_pk_mul_f32 v[190:191], v[138:139], v[174:175] op_sel_hi:[1,0]
	v_add_u32_e32 v151, 0xa0, v175
	v_pk_mul_f32 v[176:177], v[176:177], v[190:191]
	v_pk_mul_f32 v[190:191], v[136:137], v[174:175] op_sel_hi:[1,0]
	s_nop 0
	v_pk_mul_f32 v[188:189], v[188:189], v[190:191]
	v_pk_mul_f32 v[190:191], v[134:135], v[174:175] op_sel_hi:[1,0]
	v_cvt_pk_bf16_f32 v188, v188, v189
	v_pk_mul_f32 v[190:191], v[186:187], v[190:191]
	v_cvt_pk_bf16_f32 v187, v176, v177
	v_mad_i64_i32 v[176:177], s[2:3], v151, s81, v[162:163]
	v_cvt_pk_bf16_f32 v186, v184, v185
	v_lshl_add_u64 v[184:185], v[176:177], 0, v[164:165]
	ds_bpermute_b32 v176, v150, v208 offset:192
	v_cvt_pk_bf16_f32 v189, v190, v191
	v_cvt_f32_i32_e32 v191, v69
	v_cvt_f32_i32_e32 v190, v68
	global_store_dwordx4 v[184:185], v[186:189], off
	v_cvt_f32_i32_e32 v151, v75
	v_cvt_f32_i32_e32 v150, v74
	v_cvt_f32_i32_e32 v187, v73
	v_cvt_f32_i32_e32 v186, v72
	v_cvt_f32_i32_e32 v189, v71
	v_cvt_f32_i32_e32 v188, v70
	s_waitcnt lgkmcnt(0)
	v_pk_mul_f32 v[136:137], v[136:137], v[176:177] op_sel_hi:[1,0]
	v_pk_mul_f32 v[132:133], v[132:133], v[176:177] op_sel_hi:[1,0]
	v_pk_mul_f32 v[138:139], v[138:139], v[176:177] op_sel_hi:[1,0]
	v_pk_mul_f32 v[136:137], v[190:191], v[136:137]
	v_pk_mul_f32 v[134:135], v[134:135], v[176:177] op_sel_hi:[1,0]
	v_pk_mul_f32 v[132:133], v[186:187], v[132:133]
	v_pk_mul_f32 v[138:139], v[150:151], v[138:139]
	v_pk_mul_f32 v[150:151], v[188:189], v[134:135]
	v_cvt_pk_bf16_f32 v134, v136, v137
	v_mad_i64_i32 v[136:137], s[2:3], v153, s81, v[162:163]
	v_cvt_pk_bf16_f32 v132, v132, v133
	v_cvt_pk_bf16_f32 v133, v138, v139
	v_cvt_pk_bf16_f32 v135, v150, v151
	v_lshl_add_u64 v[136:137], v[136:137], 0, v[164:165]
	global_store_dwordx4 v[136:137], v[132:135], off
	s_nop 1
	v_mov_b32_e32 v132, v236
	v_mov_b32_e32 v133, v237
	v_mov_b32_e32 v134, v238
	v_mov_b32_e32 v135, v239
	v_mov_b32_e32 v136, v240
	v_mov_b32_e32 v137, v241
	v_mov_b32_e32 v138, v242
	v_mov_b32_e32 v139, v243
	v_cvt_f32_i32_e32 v189, v59
	v_cvt_f32_i32_e32 v188, v58
	v_cvt_f32_i32_e32 v187, v61
	v_cvt_f32_i32_e32 v186, v60
	v_mad_i64_i32 v[150:151], s[2:3], v153, s81, 0
	v_pk_mul_f32 v[132:133], v[132:133], s[6:7] op_sel_hi:[1,0]
	v_pk_mul_f32 v[164:165], v[138:139], s[6:7] op_sel_hi:[1,0]
	v_cvt_f32_i32_e32 v139, v63
	v_cvt_f32_i32_e32 v138, v62
	v_pk_mul_f32 v[162:163], v[136:137], s[6:7] op_sel_hi:[1,0]
	v_cvt_f32_i32_e32 v137, v65
	v_cvt_f32_i32_e32 v136, v64
;     template <int KIND>
;     __device__ __forceinline__ void run(const f32x4 (&acc)[2][2][4][2], const Unit& u, int wr, int wc, int fr, int fq) const {
;         const int row0 = u.pm * BM + wr * 64 + fr, col0 = u.pn * BM + wc * 32 + 8 * fq;
;         const float sa_lo = sa[u.pm * BM + wr * 64 + fr + 16 * fq], sa_hi = sa[u.pm * BM + HALF + wr * 64 + fr + 16 * fq];
; #pragma unroll
;         for (int bj = 0; bj < 2; ++bj) {
;             f32x2_t sc2[4], aux2[4];
; #pragma unroll
;             for (int j = 0; j < 4; ++j) {
;                 const float k0 = (KIND == 4) ? (0.125f * LOG2E / 127.0f) : (1.0f / 127.0f);
;                 sc2[j] = (f32x2_t){wmax[col0 + bj * HALF + 2 * j] * k0, wmax[col0 + bj * HALF + 2 * j + 1] * k0};
;                 if (KIND == 1) aux2[j] = (f32x2_t){lb[col0 - C_HG + bj * HALF + 2 * j], lb[col0 - C_HG + bj * HALF + 2 * j + 1]};
;                 else if (KIND == 3) aux2[j] = (f32x2_t){gain[col0 - C_HGATE + bj * HALF + 2 * j], gain[col0 - C_HGATE + bj * HALF + 2 * j + 1]};
;                 else aux2[j] = (f32x2_t){0.f, 0.f};
;             }
; #pragma unroll
;             for (int ai = 0; ai < 2; ++ai)
; #pragma unroll
;                 for (int m = 0; m < 4; ++m) { const int row = row0 + ai * HALF + m * 16; const float a = __shfl(ai ? sa_hi : sa_lo, 16 * m + fr);
;                     const f32x4 f0 = __builtin_convertvector(__builtin_bit_cast(i32x4, acc[ai][bj][m][0]), f32x4), f1 = __builtin_convertvector(__builtin_bit_cast(i32x4, acc[ai][bj][m][1]), f32x4);
;                     f32x2_t v[4] = {(f32x2_t){f0[0], f0[1]}, (f32x2_t){f0[2], f0[3]}, (f32x2_t){f1[0], f1[1]}, (f32x2_t){f1[2], f1[3]}};
; #pragma unroll
;                     for (int j = 0; j < 4; ++j) {
;                         v[j] = v[j] * (sc2[j] * (f32x2_t){a, a});
;                         if (KIND == 0 || KIND == 1 || KIND == 3) {
;                             const f32x2_t e = v[j] * (f32x2_t){-LOG2E, -LOG2E};
;                             const f32x2_t dn = (f32x2_t){__builtin_amdgcn_exp2f(e[0]), __builtin_amdgcn_exp2f(e[1])} + (f32x2_t){1.0f, 1.0f};
;                             const f32x2_t sg = (f32x2_t){fast_rcp(dn[0]), fast_rcp(dn[1])};
;                             if (KIND == 0) v[j] = v[j] * sg;
;                             else if (KIND == 3) v[j] = (v[j] * sg) * aux2[j];
	v_pk_mul_f32 v[190:191], v[66:67], v[162:163] op_sel_hi:[0,1]
	v_pk_mul_f32 v[138:139], v[138:139], v[190:191]
	v_pk_mul_f32 v[190:191], v[66:67], v[164:165] op_sel_hi:[0,1]
	v_pk_mul_f32 v[134:135], v[134:135], s[6:7] op_sel_hi:[1,0]
	v_pk_mul_f32 v[190:191], v[136:137], v[190:191]
	v_pk_mul_f32 v[136:137], v[66:67], v[132:133] op_sel_hi:[0,1]
	v_pk_mul_f32 v[188:189], v[188:189], v[136:137]
	v_pk_mul_f32 v[136:137], v[66:67], v[134:135] op_sel_hi:[0,1]
	v_pk_mul_f32 v[186:187], v[186:187], v[136:137]
	v_cvt_pk_bf16_f32 v136, v138, v139
	v_cvt_pk_bf16_f32 v137, v190, v191
	v_cvt_pk_bf16_f32 v138, v188, v189
	v_cvt_pk_bf16_f32 v139, v186, v187
	global_store_dwordx4 v[156:157], v[136:139], off offset:256
	v_cvt_f32_i32_e32 v187, v51
	v_cvt_f32_i32_e32 v186, v50
	v_cvt_f32_i32_e32 v139, v55
	v_cvt_f32_i32_e32 v138, v54
	v_cvt_f32_i32_e32 v137, v57
	v_cvt_f32_i32_e32 v136, v56
	v_cvt_f32_i32_e32 v157, v53
	v_cvt_f32_i32_e32 v156, v52
	v_pk_mul_f32 v[188:189], v[152:153], v[162:163] op_sel_hi:[0,1]
	v_pk_mul_f32 v[138:139], v[138:139], v[188:189]
	v_pk_mul_f32 v[188:189], v[152:153], v[164:165] op_sel_hi:[0,1]
	v_pk_mul_f32 v[188:189], v[136:137], v[188:189]
	v_pk_mul_f32 v[136:137], v[152:153], v[132:133] op_sel_hi:[0,1]
	v_pk_mul_f32 v[186:187], v[186:187], v[136:137]
	v_pk_mul_f32 v[136:137], v[152:153], v[134:135] op_sel_hi:[0,1]
	v_pk_mul_f32 v[152:153], v[156:157], v[136:137]
	v_cvt_pk_bf16_f32 v136, v138, v139
	v_cvt_pk_bf16_f32 v137, v188, v189
	v_cvt_pk_bf16_f32 v138, v186, v187
	v_cvt_pk_bf16_f32 v139, v152, v153
	global_store_dwordx4 v[160:161], v[136:139], off offset:256
	v_cvt_f32_i32_e32 v157, v43
	v_cvt_f32_i32_e32 v156, v42
	v_cvt_f32_i32_e32 v139, v47
	v_cvt_f32_i32_e32 v138, v46
	v_cvt_f32_i32_e32 v137, v49
	v_cvt_f32_i32_e32 v136, v48
	v_cvt_f32_i32_e32 v153, v45
	v_cvt_f32_i32_e32 v152, v44
	v_pk_mul_f32 v[160:161], v[158:159], v[162:163] op_sel_hi:[0,1]
	v_pk_mul_f32 v[138:139], v[138:139], v[160:161]
	v_pk_mul_f32 v[160:161], v[158:159], v[164:165] op_sel_hi:[0,1]
	v_pk_mul_f32 v[160:161], v[136:137], v[160:161]
	v_pk_mul_f32 v[136:137], v[158:159], v[132:133] op_sel_hi:[0,1]
	v_pk_mul_f32 v[156:157], v[156:157], v[136:137]
	v_pk_mul_f32 v[136:137], v[158:159], v[134:135] op_sel_hi:[0,1]
	v_pk_mul_f32 v[152:153], v[152:153], v[136:137]
	v_cvt_pk_bf16_f32 v136, v138, v139
	v_cvt_pk_bf16_f32 v137, v160, v161
	v_cvt_pk_bf16_f32 v138, v156, v157
	v_cvt_pk_bf16_f32 v139, v152, v153
	global_store_dwordx4 v[166:167], v[136:139], off offset:256
	v_cvt_f32_i32_e32 v157, v35
	v_cvt_f32_i32_e32 v156, v34
	v_cvt_f32_i32_e32 v139, v39
	v_cvt_f32_i32_e32 v138, v38
	v_cvt_f32_i32_e32 v137, v41
	v_cvt_f32_i32_e32 v136, v40
	v_cvt_f32_i32_e32 v153, v37
	v_cvt_f32_i32_e32 v152, v36
	v_pk_mul_f32 v[158:159], v[168:169], v[162:163] op_sel_hi:[0,1]
	v_pk_mul_f32 v[138:139], v[138:139], v[158:159]
	v_pk_mul_f32 v[158:159], v[168:169], v[164:165] op_sel_hi:[0,1]
	v_pk_mul_f32 v[158:159], v[136:137], v[158:159]
	v_pk_mul_f32 v[136:137], v[168:169], v[132:133] op_sel_hi:[0,1]
	v_pk_mul_f32 v[156:157], v[156:157], v[136:137]
	v_pk_mul_f32 v[136:137], v[168:169], v[134:135] op_sel_hi:[0,1]
	v_pk_mul_f32 v[152:153], v[152:153], v[136:137]
	v_cvt_pk_bf16_f32 v136, v138, v139
	v_cvt_pk_bf16_f32 v137, v158, v159
	v_cvt_pk_bf16_f32 v138, v156, v157
	v_cvt_pk_bf16_f32 v139, v152, v153
	global_store_dwordx4 v[178:179], v[136:139], off offset:256
	v_cvt_f32_i32_e32 v157, v27
	v_cvt_f32_i32_e32 v156, v26
	v_cvt_f32_i32_e32 v139, v31
	v_cvt_f32_i32_e32 v138, v30
	v_cvt_f32_i32_e32 v137, v33
	v_cvt_f32_i32_e32 v136, v32
	v_cvt_f32_i32_e32 v153, v29
	v_cvt_f32_i32_e32 v152, v28
	v_pk_mul_f32 v[158:159], v[170:171], v[162:163] op_sel_hi:[0,1]
	v_pk_mul_f32 v[138:139], v[138:139], v[158:159]
	v_pk_mul_f32 v[158:159], v[170:171], v[164:165] op_sel_hi:[0,1]
	v_pk_mul_f32 v[158:159], v[136:137], v[158:159]
	v_pk_mul_f32 v[136:137], v[170:171], v[132:133] op_sel_hi:[0,1]
	v_pk_mul_f32 v[156:157], v[156:157], v[136:137]
	v_pk_mul_f32 v[136:137], v[170:171], v[134:135] op_sel_hi:[0,1]
	v_pk_mul_f32 v[152:153], v[152:153], v[136:137]
	v_cvt_pk_bf16_f32 v136, v138, v139
	v_cvt_pk_bf16_f32 v137, v158, v159
	v_cvt_pk_bf16_f32 v138, v156, v157
	v_cvt_pk_bf16_f32 v139, v152, v153
	global_store_dwordx4 v[180:181], v[136:139], off offset:256
	v_cvt_f32_i32_e32 v157, v19
	v_cvt_f32_i32_e32 v156, v18
	v_cvt_f32_i32_e32 v139, v23
	v_cvt_f32_i32_e32 v138, v22
	v_cvt_f32_i32_e32 v137, v25
	v_cvt_f32_i32_e32 v136, v24
	v_cvt_f32_i32_e32 v153, v21
	v_cvt_f32_i32_e32 v152, v20
	v_pk_mul_f32 v[158:159], v[172:173], v[162:163] op_sel_hi:[0,1]
	v_pk_mul_f32 v[138:139], v[138:139], v[158:159]
	v_pk_mul_f32 v[158:159], v[172:173], v[164:165] op_sel_hi:[0,1]
	v_pk_mul_f32 v[158:159], v[136:137], v[158:159]
	v_pk_mul_f32 v[136:137], v[172:173], v[132:133] op_sel_hi:[0,1]
	v_pk_mul_f32 v[156:157], v[156:157], v[136:137]
	v_pk_mul_f32 v[136:137], v[172:173], v[134:135] op_sel_hi:[0,1]
	v_pk_mul_f32 v[152:153], v[152:153], v[136:137]
	v_cvt_pk_bf16_f32 v136, v138, v139
	v_cvt_pk_bf16_f32 v137, v158, v159
	v_cvt_pk_bf16_f32 v138, v156, v157
	v_cvt_pk_bf16_f32 v139, v152, v153
	global_store_dwordx4 v[182:183], v[136:139], off offset:256
	v_cvt_f32_i32_e32 v157, v11
	v_cvt_f32_i32_e32 v156, v10
	v_cvt_f32_i32_e32 v139, v15
	v_cvt_f32_i32_e32 v138, v14
	v_cvt_f32_i32_e32 v137, v17
	v_cvt_f32_i32_e32 v136, v16
	v_cvt_f32_i32_e32 v153, v13
	v_cvt_f32_i32_e32 v152, v12
	v_pk_mul_f32 v[158:159], v[174:175], v[162:163] op_sel_hi:[0,1]
	v_pk_mul_f32 v[138:139], v[138:139], v[158:159]
	v_pk_mul_f32 v[158:159], v[174:175], v[164:165] op_sel_hi:[0,1]
	v_pk_mul_f32 v[158:159], v[136:137], v[158:159]
	v_pk_mul_f32 v[136:137], v[174:175], v[132:133] op_sel_hi:[0,1]
	v_pk_mul_f32 v[156:157], v[156:157], v[136:137]
	v_pk_mul_f32 v[136:137], v[174:175], v[134:135] op_sel_hi:[0,1]
	v_pk_mul_f32 v[152:153], v[152:153], v[136:137]
	v_cvt_pk_bf16_f32 v136, v138, v139
	v_cvt_pk_bf16_f32 v137, v158, v159
	v_cvt_pk_bf16_f32 v138, v156, v157
	v_cvt_pk_bf16_f32 v139, v152, v153
	global_store_dwordx4 v[184:185], v[136:139], off offset:256
	v_cvt_f32_i32_e32 v153, v5
	v_cvt_f32_i32_e32 v152, v4
	v_cvt_f32_i32_e32 v137, v7
	v_cvt_f32_i32_e32 v136, v6
	v_cvt_f32_i32_e32 v139, v9
	v_cvt_f32_i32_e32 v138, v8
	v_cvt_f32_i32_e32 v157, v3
	v_cvt_f32_i32_e32 v156, v2
	v_pk_mul_f32 v[158:159], v[176:177], v[162:163] op_sel_hi:[0,1]
	v_pk_mul_f32 v[136:137], v[136:137], v[158:159]
	v_pk_mul_f32 v[158:159], v[176:177], v[164:165] op_sel_hi:[0,1]
	v_pk_mul_f32 v[132:133], v[176:177], v[132:133] op_sel_hi:[0,1]
	v_pk_mul_f32 v[134:135], v[176:177], v[134:135] op_sel_hi:[0,1]
	v_pk_mul_f32 v[138:139], v[138:139], v[158:159]
	v_pk_mul_f32 v[132:133], v[156:157], v[132:133]
	v_pk_mul_f32 v[134:135], v[152:153], v[134:135]

;     template <int KIND>
;     __device__ __forceinline__ void run(const f32x4 (&acc)[2][2][4][2], const Unit& u, int wr, int wc, int fr, int fq) const {
;         const int row0 = u.pm * BM + wr * 64 + fr, col0 = u.pn * BM + wc * 32 + 8 * fq;
;         const float sa_lo = sa[u.pm * BM + wr * 64 + fr + 16 * fq], sa_hi = sa[u.pm * BM + HALF + wr * 64 + fr + 16 * fq];
; #pragma unroll
;         for (int bj = 0; bj < 2; ++bj) {
;             f32x2_t sc2[4], aux2[4];
; #pragma unroll
;             for (int j = 0; j < 4; ++j) {
;                 const float k0 = (KIND == 4) ? (0.125f * LOG2E / 127.0f) : (1.0f / 127.0f);
;                 sc2[j] = (f32x2_t){wmax[col0 + bj * HALF + 2 * j] * k0, wmax[col0 + bj * HALF + 2 * j + 1] * k0};
;                 if (KIND == 1) aux2[j] = (f32x2_t){lb[col0 - C_HG + bj * HALF + 2 * j], lb[col0 - C_HG + bj * HALF + 2 * j + 1]};
;                 else if (KIND == 3) aux2[j] = (f32x2_t){gain[col0 - C_HGATE + bj * HALF + 2 * j], gain[col0 - C_HGATE + bj * HALF + 2 * j + 1]};
;                 else aux2[j] = (f32x2_t){0.f, 0.f};
;             }
; #pragma unroll
;             for (int ai = 0; ai < 2; ++ai)
; #pragma unroll
;                 for (int m = 0; m < 4; ++m) { const int row = row0 + ai * HALF + m * 16; const float a = __shfl(ai ? sa_hi : sa_lo, 16 * m + fr);
;                     const f32x4 f0 = __builtin_convertvector(__builtin_bit_cast(i32x4, acc[ai][bj][m][0]), f32x4), f1 = __builtin_convertvector(__builtin_bit_cast(i32x4, acc[ai][bj][m][1]), f32x4);
;                     f32x2_t v[4] = {(f32x2_t){f0[0], f0[1]}, (f32x2_t){f0[2], f0[3]}, (f32x2_t){f1[0], f1[1]}, (f32x2_t){f1[2], f1[3]}};
; #pragma unroll
;                     for (int j = 0; j < 4; ++j) {
;                         v[j] = v[j] * (sc2[j] * (f32x2_t){a, a});
;                         if (KIND == 0 || KIND == 1 || KIND == 3) {
;                             const f32x2_t e = v[j] * (f32x2_t){-LOG2E, -LOG2E};
;                             const f32x2_t dn = (f32x2_t){__builtin_amdgcn_exp2f(e[0]), __builtin_amdgcn_exp2f(e[1])} + (f32x2_t){1.0f, 1.0f};
;                             const f32x2_t sg = (f32x2_t){fast_rcp(dn[0]), fast_rcp(dn[1])};
;                             if (KIND == 0) v[j] = v[j] * sg;
;                             else if (KIND == 3) v[j] = (v[j] * sg) * aux2[j];
.LBB0_212:
	s_and_b64 vcc, exec, s[0:1]
	s_cbranch_vccz .LBB0_214
	s_lshl_b32 s0, s90, 8
	v_add_u32_e32 v133, s0, v212
	v_or_b32_e32 v134, v133, v214
	v_ashrrev_i32_e32 v135, 31, v134
	v_lshl_add_u64 v[134:135], v[134:135], 2, s[46:47]
	global_load_dword v154, v[134:135], off
	v_add_u32_e32 v134, s0, v215
	v_ashrrev_i32_e32 v135, 31, v134
	v_lshl_add_u64 v[134:135], v[134:135], 2, s[46:47]
	v_mov_b32_e32 v147, v67
	global_load_dword v152, v[134:135], off
	v_lshl_add_u64 v[134:135], v[146:147], 2, s[48:49]
	global_load_dwordx4 v[156:159], v[134:135], off offset:16
	global_load_dwordx4 v[136:139], v[134:135], off
	global_load_dwordx4 v[236:239], v[134:135], off offset:528
	global_load_dwordx4 v[240:243], v[134:135], off offset:512
	v_lshlrev_b32_e32 v153, 2, v233
	v_cvt_f32_i32_e32 v129, v129
	v_cvt_f32_i32_e32 v128, v128
	s_mov_b32 s2, 0x3c010204
	s_mov_b32 s6, 0xbfb8aa3b
	v_cvt_f32_i32_e32 v131, v131
	v_cvt_f32_i32_e32 v130, v130
	v_cvt_f32_i32_e32 v125, v125
	v_cvt_f32_i32_e32 v124, v124
	v_cvt_f32_i32_e32 v127, v127
	v_cvt_f32_i32_e32 v126, v126
	v_lshlrev_b32_e32 v66, 1, v146
	v_cvt_f32_i32_e32 v121, v121
	v_cvt_f32_i32_e32 v120, v120
	v_cvt_f32_i32_e32 v123, v123
	v_cvt_f32_i32_e32 v122, v122
	v_cvt_f32_i32_e32 v119, v119
	v_cvt_f32_i32_e32 v118, v118
	v_cvt_f32_i32_e32 v113, v113
	v_cvt_f32_i32_e32 v112, v112
	v_cvt_f32_i32_e32 v115, v115
	v_cvt_f32_i32_e32 v114, v114
	v_cvt_f32_i32_e32 v109, v109
	v_cvt_f32_i32_e32 v108, v108
	v_cvt_f32_i32_e32 v111, v111
	v_cvt_f32_i32_e32 v110, v110
	v_cvt_f32_i32_e32 v105, v105
	v_cvt_f32_i32_e32 v104, v104
	v_cvt_f32_i32_e32 v107, v107
	v_cvt_f32_i32_e32 v106, v106
	v_cvt_f32_i32_e32 v101, v101
	v_cvt_f32_i32_e32 v100, v100
	v_cvt_f32_i32_e32 v103, v103
	v_cvt_f32_i32_e32 v102, v102
	v_cvt_f32_i32_e32 v97, v97
	v_cvt_f32_i32_e32 v96, v96
	v_cvt_f32_i32_e32 v99, v99
	v_cvt_f32_i32_e32 v98, v98
	v_cvt_f32_i32_e32 v93, v93
	v_cvt_f32_i32_e32 v92, v92
	v_cvt_f32_i32_e32 v95, v95
	v_cvt_f32_i32_e32 v94, v94
	v_cvt_f32_i32_e32 v89, v89
	v_cvt_f32_i32_e32 v88, v88
	v_cvt_f32_i32_e32 v91, v91
	v_cvt_f32_i32_e32 v90, v90
	v_cvt_f32_i32_e32 v85, v85
	v_cvt_f32_i32_e32 v84, v84
	v_cvt_f32_i32_e32 v87, v87
	v_cvt_f32_i32_e32 v86, v86
	v_cvt_f32_i32_e32 v81, v81
	v_cvt_f32_i32_e32 v80, v80
	v_cvt_f32_i32_e32 v83, v83
	v_cvt_f32_i32_e32 v82, v82
	v_cvt_f32_i32_e32 v77, v77
	v_cvt_f32_i32_e32 v76, v76
	v_cvt_f32_i32_e32 v79, v79
	v_cvt_f32_i32_e32 v78, v78
	v_cvt_f32_i32_e32 v73, v73
	v_cvt_f32_i32_e32 v72, v72
	v_cvt_f32_i32_e32 v75, v75
	v_cvt_f32_i32_e32 v74, v74
	v_cvt_f32_i32_e32 v69, v69
	v_cvt_f32_i32_e32 v68, v68
	v_cvt_f32_i32_e32 v71, v71
	v_cvt_f32_i32_e32 v70, v70
	v_cvt_f32_i32_e32 v63, v63
	v_cvt_f32_i32_e32 v62, v62
	v_cvt_f32_i32_e32 v65, v65
	v_cvt_f32_i32_e32 v64, v64
	v_cvt_f32_i32_e32 v59, v59
	v_cvt_f32_i32_e32 v58, v58
	s_waitcnt vmcnt(0)
	ds_bpermute_b32 v132, v153, v154
	v_cvt_f32_i32_e32 v61, v61
	v_cvt_f32_i32_e32 v60, v60
	v_cvt_f32_i32_e32 v55, v55
	v_cvt_f32_i32_e32 v54, v54
	v_cvt_f32_i32_e32 v57, v57
	v_cvt_f32_i32_e32 v56, v56
	v_pk_mul_f32 v[150:151], v[136:137], s[2:3] op_sel_hi:[1,0]
	v_pk_mul_f32 v[148:149], v[138:139], s[2:3] op_sel_hi:[1,0]
	v_pk_mul_f32 v[138:139], v[156:157], s[2:3] op_sel_hi:[1,0]
	s_waitcnt lgkmcnt(0)
	v_pk_mul_f32 v[156:157], v[150:151], v[132:133] op_sel_hi:[1,0]
	v_pk_mul_f32 v[136:137], v[158:159], s[2:3] op_sel_hi:[1,0]
	v_pk_mul_f32 v[128:129], v[128:129], v[156:157]
	v_cvt_f32_i32_e32 v51, v51
	v_pk_mul_f32 v[156:157], v[128:129], s[6:7] op_sel_hi:[1,0]
	v_cvt_f32_i32_e32 v50, v50
	v_exp_f32_e32 v156, v156
	v_exp_f32_e32 v157, v157
	v_cvt_f32_i32_e32 v53, v53
	v_cvt_f32_i32_e32 v52, v52
	v_cvt_f32_i32_e32 v47, v47
	v_pk_add_f32 v[156:157], v[156:157], 1.0 op_sel_hi:[1,0]
	v_cvt_f32_i32_e32 v46, v46
	v_rcp_f32_e32 v156, v156
	v_rcp_f32_e32 v157, v157
	v_cvt_f32_i32_e32 v49, v49
	v_cvt_f32_i32_e32 v48, v48
	v_cvt_f32_i32_e32 v43, v43
	v_pk_mul_f32 v[128:129], v[128:129], v[156:157]
	v_pk_mul_f32 v[156:157], v[148:149], v[132:133] op_sel_hi:[1,0]
	v_cvt_f32_i32_e32 v42, v42
	v_pk_mul_f32 v[130:131], v[130:131], v[156:157]
	v_cvt_f32_i32_e32 v45, v45
	v_pk_mul_f32 v[156:157], v[130:131], s[6:7] op_sel_hi:[1,0]
	v_cvt_f32_i32_e32 v44, v44
	v_exp_f32_e32 v156, v156
	v_exp_f32_e32 v157, v157
	v_cvt_f32_i32_e32 v39, v39
	v_cvt_f32_i32_e32 v38, v38
	v_cvt_f32_i32_e32 v41, v41
	v_pk_add_f32 v[156:157], v[156:157], 1.0 op_sel_hi:[1,0]
	v_cvt_f32_i32_e32 v40, v40
	v_rcp_f32_e32 v156, v156
	v_rcp_f32_e32 v157, v157
	v_cvt_f32_i32_e32 v35, v35
	v_cvt_f32_i32_e32 v34, v34
	v_cvt_f32_i32_e32 v37, v37
	v_pk_mul_f32 v[130:131], v[130:131], v[156:157]
	v_pk_mul_f32 v[156:157], v[138:139], v[132:133] op_sel_hi:[1,0]
	v_cvt_f32_i32_e32 v36, v36
	v_pk_mul_f32 v[124:125], v[124:125], v[156:157]
	v_cvt_f32_i32_e32 v31, v31
	v_pk_mul_f32 v[156:157], v[124:125], s[6:7] op_sel_hi:[1,0]
	v_cvt_f32_i32_e32 v30, v30
	v_exp_f32_e32 v156, v156
	v_exp_f32_e32 v157, v157
	v_cvt_f32_i32_e32 v33, v33
	v_cvt_f32_i32_e32 v32, v32
	v_cvt_f32_i32_e32 v27, v27
	v_pk_add_f32 v[156:157], v[156:157], 1.0 op_sel_hi:[1,0]
	v_cvt_f32_i32_e32 v26, v26
	v_rcp_f32_e32 v156, v156
	v_rcp_f32_e32 v157, v157
	v_cvt_f32_i32_e32 v29, v29
	v_cvt_f32_i32_e32 v28, v28
	v_cvt_f32_i32_e32 v23, v23
	v_pk_mul_f32 v[124:125], v[124:125], v[156:157]
	v_pk_mul_f32 v[156:157], v[136:137], v[132:133] op_sel_hi:[1,0]
	v_cvt_pk_bf16_f32 v158, v124, v125
	v_pk_mul_f32 v[126:127], v[126:127], v[156:157]
	v_cvt_f32_i32_e32 v22, v22
	v_pk_mul_f32 v[156:157], v[126:127], s[6:7] op_sel_hi:[1,0]
	v_cvt_f32_i32_e32 v25, v25
	v_exp_f32_e32 v156, v156
	v_exp_f32_e32 v157, v157
	v_cvt_f32_i32_e32 v24, v24
	v_cvt_f32_i32_e32 v19, v19
	v_cvt_f32_i32_e32 v18, v18
	v_pk_add_f32 v[156:157], v[156:157], 1.0 op_sel_hi:[1,0]
	v_cvt_f32_i32_e32 v21, v21
	v_rcp_f32_e32 v156, v156
	v_rcp_f32_e32 v157, v157
	v_cvt_f32_i32_e32 v20, v20
	v_cvt_f32_i32_e32 v15, v15
	v_cvt_f32_i32_e32 v14, v14
	v_pk_mul_f32 v[126:127], v[126:127], v[156:157]
	v_cvt_pk_bf16_f32 v156, v128, v129
	v_mov_b64_e32 v[128:129], s[14:15]
	v_mad_i64_i32 v[124:125], s[0:1], v133, s81, v[128:129]
	v_cvt_pk_bf16_f32 v159, v126, v127
	v_lshl_add_u64 v[126:127], v[124:125], 0, v[66:67]
	ds_bpermute_b32 v124, v153, v154 offset:64
	v_cvt_pk_bf16_f32 v157, v130, v131
	v_cvt_f32_i32_e32 v131, v117
	v_cvt_f32_i32_e32 v130, v116
	global_store_dwordx4 v[126:127], v[156:159], off
	s_waitcnt lgkmcnt(0)
;     template <int KIND>
;     __device__ __forceinline__ void run(const f32x4 (&acc)[2][2][4][2], const Unit& u, int wr, int wc, int fr, int fq) const {
;         const int row0 = u.pm * BM + wr * 64 + fr, col0 = u.pn * BM + wc * 32 + 8 * fq;
;         const float sa_lo = sa[u.pm * BM + wr * 64 + fr + 16 * fq], sa_hi = sa[u.pm * BM + HALF + wr * 64 + fr + 16 * fq];
; #pragma unroll
;         for (int bj = 0; bj < 2; ++bj) {
;             f32x2_t sc2[4], aux2[4];
; #pragma unroll
;             for (int j = 0; j < 4; ++j) {
;                 const float k0 = (KIND == 4) ? (0.125f * LOG2E / 127.0f) : (1.0f / 127.0f);
;                 sc2[j] = (f32x2_t){wmax[col0 + bj * HALF + 2 * j] * k0, wmax[col0 + bj * HALF + 2 * j + 1] * k0};
;                 if (KIND == 1) aux2[j] = (f32x2_t){lb[col0 - C_HG + bj * HALF + 2 * j], lb[col0 - C_HG + bj * HALF + 2 * j + 1]};
;                 else if (KIND == 3) aux2[j] = (f32x2_t){gain[col0 - C_HGATE + bj * HALF + 2 * j], gain[col0 - C_HGATE + bj * HALF + 2 * j + 1]};
;                 else aux2[j] = (f32x2_t){0.f, 0.f};
;             }
; #pragma unroll
;             for (int ai = 0; ai < 2; ++ai)
; #pragma unroll
;                 for (int m = 0; m < 4; ++m) { const int row = row0 + ai * HALF + m * 16; const float a = __shfl(ai ? sa_hi : sa_lo, 16 * m + fr);
;                     const f32x4 f0 = __builtin_convertvector(__builtin_bit_cast(i32x4, acc[ai][bj][m][0]), f32x4), f1 = __builtin_convertvector(__builtin_bit_cast(i32x4, acc[ai][bj][m][1]), f32x4);
;                     f32x2_t v[4] = {(f32x2_t){f0[0], f0[1]}, (f32x2_t){f0[2], f0[3]}, (f32x2_t){f1[0], f1[1]}, (f32x2_t){f1[2], f1[3]}};
; #pragma unroll
;                     for (int j = 0; j < 4; ++j) {
;                         v[j] = v[j] * (sc2[j] * (f32x2_t){a, a});
;                         if (KIND == 0 || KIND == 1 || KIND == 3) {
;                             const f32x2_t e = v[j] * (f32x2_t){-LOG2E, -LOG2E};
;                             const f32x2_t dn = (f32x2_t){__builtin_amdgcn_exp2f(e[0]), __builtin_amdgcn_exp2f(e[1])} + (f32x2_t){1.0f, 1.0f};
;                             const f32x2_t sg = (f32x2_t){fast_rcp(dn[0]), fast_rcp(dn[1])};
;                             if (KIND == 0) v[j] = v[j] * sg;
;                             else if (KIND == 3) v[j] = (v[j] * sg) * aux2[j];
	v_pk_mul_f32 v[116:117], v[150:151], v[124:125] op_sel_hi:[1,0]
	v_cvt_f32_i32_e32 v17, v17
	v_pk_mul_f32 v[116:117], v[120:121], v[116:117]
	v_cvt_f32_i32_e32 v16, v16
	v_pk_mul_f32 v[120:121], v[116:117], s[6:7] op_sel_hi:[1,0]
	v_cvt_f32_i32_e32 v11, v11
	v_exp_f32_e32 v120, v120
	v_exp_f32_e32 v121, v121
	v_cvt_f32_i32_e32 v10, v10
	v_cvt_f32_i32_e32 v13, v13
	v_cvt_f32_i32_e32 v12, v12
	v_pk_add_f32 v[120:121], v[120:121], 1.0 op_sel_hi:[1,0]
	v_cvt_f32_i32_e32 v7, v7
	v_rcp_f32_e32 v120, v120
	v_rcp_f32_e32 v121, v121
	v_cvt_f32_i32_e32 v6, v6
	v_cvt_f32_i32_e32 v9, v9
	v_cvt_f32_i32_e32 v8, v8
	v_pk_mul_f32 v[116:117], v[116:117], v[120:121]
	v_pk_mul_f32 v[120:121], v[148:149], v[124:125] op_sel_hi:[1,0]
	v_cvt_pk_bf16_f32 v156, v116, v117
	v_pk_mul_f32 v[120:121], v[122:123], v[120:121]
	v_cvt_f32_i32_e32 v3, v3
	v_pk_mul_f32 v[122:123], v[120:121], s[6:7] op_sel_hi:[1,0]
	v_cvt_f32_i32_e32 v2, v2
	v_exp_f32_e32 v122, v122
	v_exp_f32_e32 v123, v123
	v_cvt_f32_i32_e32 v5, v5
	v_cvt_f32_i32_e32 v4, v4
	v_pk_add_f32 v[122:123], v[122:123], 1.0 op_sel_hi:[1,0]
	s_nop 0
	v_rcp_f32_e32 v122, v122
	v_rcp_f32_e32 v123, v123
	s_nop 0
	v_pk_mul_f32 v[120:121], v[120:121], v[122:123]
	v_pk_mul_f32 v[122:123], v[138:139], v[124:125] op_sel_hi:[1,0]
	v_cvt_pk_bf16_f32 v157, v120, v121
	v_pk_mul_f32 v[122:123], v[130:131], v[122:123]
	s_nop 0
	v_pk_mul_f32 v[130:131], v[122:123], s[6:7] op_sel_hi:[1,0]
	s_nop 0
	v_exp_f32_e32 v130, v130
	v_exp_f32_e32 v131, v131
	s_nop 0
	v_pk_add_f32 v[130:131], v[130:131], 1.0 op_sel_hi:[1,0]
	s_nop 0
	v_rcp_f32_e32 v130, v130
	v_rcp_f32_e32 v131, v131
	s_nop 0
	v_pk_mul_f32 v[122:123], v[122:123], v[130:131]
	v_pk_mul_f32 v[130:131], v[136:137], v[124:125] op_sel_hi:[1,0]
	v_or_b32_e32 v125, 16, v133
	v_pk_mul_f32 v[118:119], v[118:119], v[130:131]
	v_mad_i64_i32 v[116:117], s[0:1], v125, s81, v[128:129]
	v_pk_mul_f32 v[130:131], v[118:119], s[6:7] op_sel_hi:[1,0]
	v_cvt_pk_bf16_f32 v158, v122, v123
	v_exp_f32_e32 v130, v130
	v_exp_f32_e32 v131, v131
	s_nop 0
	v_pk_add_f32 v[130:131], v[130:131], 1.0 op_sel_hi:[1,0]
	s_nop 0
	v_rcp_f32_e32 v130, v130
	v_rcp_f32_e32 v131, v131
	s_nop 0
	v_pk_mul_f32 v[118:119], v[118:119], v[130:131]
	s_nop 0
	v_cvt_pk_bf16_f32 v159, v118, v119
	v_lshl_add_u64 v[118:119], v[116:117], 0, v[66:67]
	ds_bpermute_b32 v116, v153, v154 offset:128
	global_store_dwordx4 v[118:119], v[156:159], off
	s_waitcnt lgkmcnt(0)
	v_pk_mul_f32 v[120:121], v[150:151], v[116:117] op_sel_hi:[1,0]
	s_nop 0
	v_pk_mul_f32 v[112:113], v[112:113], v[120:121]
	s_nop 0
	v_pk_mul_f32 v[120:121], v[112:113], s[6:7] op_sel_hi:[1,0]
	s_nop 0
	v_exp_f32_e32 v120, v120
	v_exp_f32_e32 v121, v121
	s_nop 0
	v_pk_add_f32 v[120:121], v[120:121], 1.0 op_sel_hi:[1,0]
	s_nop 0
	v_rcp_f32_e32 v120, v120
	v_rcp_f32_e32 v121, v121
	s_nop 0
	v_pk_mul_f32 v[112:113], v[112:113], v[120:121]
	v_pk_mul_f32 v[120:121], v[148:149], v[116:117] op_sel_hi:[1,0]
	v_cvt_pk_bf16_f32 v112, v112, v113
	v_pk_mul_f32 v[114:115], v[114:115], v[120:121]
	s_nop 0
	v_pk_mul_f32 v[120:121], v[114:115], s[6:7] op_sel_hi:[1,0]
	s_nop 0
	v_exp_f32_e32 v120, v120
	v_exp_f32_e32 v121, v121
	s_nop 0
	v_pk_add_f32 v[120:121], v[120:121], 1.0 op_sel_hi:[1,0]
	s_nop 0
	v_rcp_f32_e32 v120, v120
	v_rcp_f32_e32 v121, v121
	s_nop 0
	v_pk_mul_f32 v[114:115], v[114:115], v[120:121]
	v_pk_mul_f32 v[120:121], v[138:139], v[116:117] op_sel_hi:[1,0]
	v_cvt_pk_bf16_f32 v113, v114, v115
	v_pk_mul_f32 v[108:109], v[108:109], v[120:121]
	s_nop 0
	v_pk_mul_f32 v[120:121], v[108:109], s[6:7] op_sel_hi:[1,0]
	s_nop 0
	v_exp_f32_e32 v120, v120
	v_exp_f32_e32 v121, v121
	s_nop 0
	v_pk_add_f32 v[120:121], v[120:121], 1.0 op_sel_hi:[1,0]
	s_nop 0
	v_rcp_f32_e32 v120, v120
	v_rcp_f32_e32 v121, v121
	s_nop 0
	v_pk_mul_f32 v[108:109], v[108:109], v[120:121]
	v_pk_mul_f32 v[120:121], v[136:137], v[116:117] op_sel_hi:[1,0]
	v_or_b32_e32 v117, 32, v133
	v_pk_mul_f32 v[110:111], v[110:111], v[120:121]
	v_cvt_pk_bf16_f32 v114, v108, v109
	v_pk_mul_f32 v[120:121], v[110:111], s[6:7] op_sel_hi:[1,0]
	v_mad_i64_i32 v[108:109], s[0:1], v117, s81, v[128:129]
	v_exp_f32_e32 v120, v120
	v_exp_f32_e32 v121, v121
	s_nop 0
	v_pk_add_f32 v[120:121], v[120:121], 1.0 op_sel_hi:[1,0]
	s_nop 0
	v_rcp_f32_e32 v120, v120
	v_rcp_f32_e32 v121, v121
	s_nop 0
	v_pk_mul_f32 v[110:111], v[110:111], v[120:121]
	s_nop 0
	v_cvt_pk_bf16_f32 v115, v110, v111
	v_lshl_add_u64 v[110:111], v[108:109], 0, v[66:67]
	ds_bpermute_b32 v108, v153, v154 offset:192
	global_store_dwordx4 v[110:111], v[112:115], off
	s_waitcnt lgkmcnt(0)
	s_nop 0
	v_pk_mul_f32 v[112:113], v[150:151], v[108:109] op_sel_hi:[1,0]
	s_nop 0
	v_pk_mul_f32 v[104:105], v[104:105], v[112:113]
	s_nop 0
	v_pk_mul_f32 v[112:113], v[104:105], s[6:7] op_sel_hi:[1,0]
	s_nop 0
	v_exp_f32_e32 v112, v112
	v_exp_f32_e32 v113, v113
	s_nop 0
	v_pk_add_f32 v[112:113], v[112:113], 1.0 op_sel_hi:[1,0]
	s_nop 0
	v_rcp_f32_e32 v112, v112
	v_rcp_f32_e32 v113, v113
	s_nop 0
	v_pk_mul_f32 v[104:105], v[104:105], v[112:113]
	v_pk_mul_f32 v[112:113], v[148:149], v[108:109] op_sel_hi:[1,0]
	v_cvt_pk_bf16_f32 v104, v104, v105
	v_pk_mul_f32 v[106:107], v[106:107], v[112:113]
	s_nop 0
	v_pk_mul_f32 v[112:113], v[106:107], s[6:7] op_sel_hi:[1,0]
	s_nop 0
	v_exp_f32_e32 v112, v112
	v_exp_f32_e32 v113, v113
	s_nop 0
	v_pk_add_f32 v[112:113], v[112:113], 1.0 op_sel_hi:[1,0]
	s_nop 0
	v_rcp_f32_e32 v112, v112
	v_rcp_f32_e32 v113, v113
	s_nop 0
	v_pk_mul_f32 v[106:107], v[106:107], v[112:113]
	v_pk_mul_f32 v[112:113], v[138:139], v[108:109] op_sel_hi:[1,0]
	v_cvt_pk_bf16_f32 v105, v106, v107
	v_pk_mul_f32 v[100:101], v[100:101], v[112:113]
	s_nop 0
	v_pk_mul_f32 v[112:113], v[100:101], s[6:7] op_sel_hi:[1,0]
	s_nop 0
	v_exp_f32_e32 v112, v112
	v_exp_f32_e32 v113, v113
	s_nop 0
	v_pk_add_f32 v[112:113], v[112:113], 1.0 op_sel_hi:[1,0]
	s_nop 0
	v_rcp_f32_e32 v112, v112
	v_rcp_f32_e32 v113, v113
	s_nop 0
	v_pk_mul_f32 v[100:101], v[100:101], v[112:113]
	v_pk_mul_f32 v[112:113], v[136:137], v[108:109] op_sel_hi:[1,0]
	v_or_b32_e32 v109, 48, v133
	v_pk_mul_f32 v[102:103], v[102:103], v[112:113]
	v_cvt_pk_bf16_f32 v106, v100, v101
	v_pk_mul_f32 v[112:113], v[102:103], s[6:7] op_sel_hi:[1,0]
	v_mad_i64_i32 v[100:101], s[0:1], v109, s81, v[128:129]
	v_exp_f32_e32 v112, v112
	v_exp_f32_e32 v113, v113
	s_nop 0
	v_pk_add_f32 v[112:113], v[112:113], 1.0 op_sel_hi:[1,0]
	s_nop 0
	v_rcp_f32_e32 v112, v112
	v_rcp_f32_e32 v113, v113
	s_nop 0
	v_pk_mul_f32 v[102:103], v[102:103], v[112:113]
	s_nop 0
	v_cvt_pk_bf16_f32 v107, v102, v103
	v_lshl_add_u64 v[102:103], v[100:101], 0, v[66:67]
	ds_bpermute_b32 v100, v153, v152
	v_add_u32_e32 v101, 0x80, v133
	global_store_dwordx4 v[102:103], v[104:107], off
	s_waitcnt lgkmcnt(0)
;     template <int KIND>
;     __device__ __forceinline__ void run(const f32x4 (&acc)[2][2][4][2], const Unit& u, int wr, int wc, int fr, int fq) const {
;         const int row0 = u.pm * BM + wr * 64 + fr, col0 = u.pn * BM + wc * 32 + 8 * fq;
;         const float sa_lo = sa[u.pm * BM + wr * 64 + fr + 16 * fq], sa_hi = sa[u.pm * BM + HALF + wr * 64 + fr + 16 * fq];
; #pragma unroll
;         for (int bj = 0; bj < 2; ++bj) {
;             f32x2_t sc2[4], aux2[4];
; #pragma unroll
;             for (int j = 0; j < 4; ++j) {
;                 const float k0 = (KIND == 4) ? (0.125f * LOG2E / 127.0f) : (1.0f / 127.0f);
;                 sc2[j] = (f32x2_t){wmax[col0 + bj * HALF + 2 * j] * k0, wmax[col0 + bj * HALF + 2 * j + 1] * k0};
;                 if (KIND == 1) aux2[j] = (f32x2_t){lb[col0 - C_HG + bj * HALF + 2 * j], lb[col0 - C_HG + bj * HALF + 2 * j + 1]};
;                 else if (KIND == 3) aux2[j] = (f32x2_t){gain[col0 - C_HGATE + bj * HALF + 2 * j], gain[col0 - C_HGATE + bj * HALF + 2 * j + 1]};
;                 else aux2[j] = (f32x2_t){0.f, 0.f};
;             }
; #pragma unroll
;             for (int ai = 0; ai < 2; ++ai)
; #pragma unroll
;                 for (int m = 0; m < 4; ++m) { const int row = row0 + ai * HALF + m * 16; const float a = __shfl(ai ? sa_hi : sa_lo, 16 * m + fr);
;                     const f32x4 f0 = __builtin_convertvector(__builtin_bit_cast(i32x4, acc[ai][bj][m][0]), f32x4), f1 = __builtin_convertvector(__builtin_bit_cast(i32x4, acc[ai][bj][m][1]), f32x4);
;                     f32x2_t v[4] = {(f32x2_t){f0[0], f0[1]}, (f32x2_t){f0[2], f0[3]}, (f32x2_t){f1[0], f1[1]}, (f32x2_t){f1[2], f1[3]}};
; #pragma unroll
;                     for (int j = 0; j < 4; ++j) {
;                         v[j] = v[j] * (sc2[j] * (f32x2_t){a, a});
;                         if (KIND == 0 || KIND == 1 || KIND == 3) {
;                             const f32x2_t e = v[j] * (f32x2_t){-LOG2E, -LOG2E};
;                             const f32x2_t dn = (f32x2_t){__builtin_amdgcn_exp2f(e[0]), __builtin_amdgcn_exp2f(e[1])} + (f32x2_t){1.0f, 1.0f};
;                             const f32x2_t sg = (f32x2_t){fast_rcp(dn[0]), fast_rcp(dn[1])};
;                             if (KIND == 0) v[j] = v[j] * sg;
;                             else if (KIND == 3) v[j] = (v[j] * sg) * aux2[j];
	s_nop 0
	v_pk_mul_f32 v[104:105], v[150:151], v[100:101] op_sel_hi:[1,0]
	s_nop 0
	v_pk_mul_f32 v[96:97], v[96:97], v[104:105]
	s_nop 0
	v_pk_mul_f32 v[104:105], v[96:97], s[6:7] op_sel_hi:[1,0]
	s_nop 0
	v_exp_f32_e32 v104, v104
	v_exp_f32_e32 v105, v105
	s_nop 0
	v_pk_add_f32 v[104:105], v[104:105], 1.0 op_sel_hi:[1,0]
	s_nop 0
	v_rcp_f32_e32 v104, v104
	v_rcp_f32_e32 v105, v105
	s_nop 0
	v_pk_mul_f32 v[96:97], v[96:97], v[104:105]
	v_pk_mul_f32 v[104:105], v[148:149], v[100:101] op_sel_hi:[1,0]
	v_cvt_pk_bf16_f32 v96, v96, v97
	v_pk_mul_f32 v[98:99], v[98:99], v[104:105]
	s_nop 0
	v_pk_mul_f32 v[104:105], v[98:99], s[6:7] op_sel_hi:[1,0]
	s_nop 0
	v_exp_f32_e32 v104, v104
	v_exp_f32_e32 v105, v105
	s_nop 0
	v_pk_add_f32 v[104:105], v[104:105], 1.0 op_sel_hi:[1,0]
	s_nop 0
	v_rcp_f32_e32 v104, v104
	v_rcp_f32_e32 v105, v105
	s_nop 0
	v_pk_mul_f32 v[98:99], v[98:99], v[104:105]
	v_pk_mul_f32 v[104:105], v[138:139], v[100:101] op_sel_hi:[1,0]
	v_cvt_pk_bf16_f32 v97, v98, v99
	v_pk_mul_f32 v[92:93], v[92:93], v[104:105]
	s_nop 0
	v_pk_mul_f32 v[104:105], v[92:93], s[6:7] op_sel_hi:[1,0]
	s_nop 0
	v_exp_f32_e32 v104, v104
	v_exp_f32_e32 v105, v105
	s_nop 0
	v_pk_add_f32 v[104:105], v[104:105], 1.0 op_sel_hi:[1,0]
	s_nop 0
	v_rcp_f32_e32 v104, v104
	v_rcp_f32_e32 v105, v105
	s_nop 0
	v_pk_mul_f32 v[92:93], v[92:93], v[104:105]
	v_pk_mul_f32 v[104:105], v[136:137], v[100:101] op_sel_hi:[1,0]
	v_cvt_pk_bf16_f32 v98, v92, v93
	v_pk_mul_f32 v[94:95], v[94:95], v[104:105]
	v_mad_i64_i32 v[92:93], s[0:1], v101, s81, v[128:129]
	v_pk_mul_f32 v[104:105], v[94:95], s[6:7] op_sel_hi:[1,0]
	s_nop 0
	v_exp_f32_e32 v104, v104
	v_exp_f32_e32 v105, v105
	s_nop 0
	v_pk_add_f32 v[104:105], v[104:105], 1.0 op_sel_hi:[1,0]
	s_nop 0
	v_rcp_f32_e32 v104, v104
	v_rcp_f32_e32 v105, v105
	s_nop 0
	v_pk_mul_f32 v[94:95], v[94:95], v[104:105]
	s_nop 0
	v_cvt_pk_bf16_f32 v99, v94, v95
	v_lshl_add_u64 v[94:95], v[92:93], 0, v[66:67]
	ds_bpermute_b32 v92, v153, v152 offset:64
	global_store_dwordx4 v[94:95], v[96:99], off
	s_waitcnt lgkmcnt(0)
	s_nop 0
	v_pk_mul_f32 v[96:97], v[150:151], v[92:93] op_sel_hi:[1,0]
	s_nop 0
	v_pk_mul_f32 v[88:89], v[88:89], v[96:97]
	s_nop 0
	v_pk_mul_f32 v[96:97], v[88:89], s[6:7] op_sel_hi:[1,0]
	s_nop 0
	v_exp_f32_e32 v96, v96
	v_exp_f32_e32 v97, v97
	s_nop 0
	v_pk_add_f32 v[96:97], v[96:97], 1.0 op_sel_hi:[1,0]
	s_nop 0
	v_rcp_f32_e32 v96, v96
	v_rcp_f32_e32 v97, v97
	s_nop 0
	v_pk_mul_f32 v[88:89], v[88:89], v[96:97]
	v_pk_mul_f32 v[96:97], v[148:149], v[92:93] op_sel_hi:[1,0]
	v_cvt_pk_bf16_f32 v88, v88, v89
	v_pk_mul_f32 v[90:91], v[90:91], v[96:97]
	s_nop 0
	v_pk_mul_f32 v[96:97], v[90:91], s[6:7] op_sel_hi:[1,0]
	s_nop 0
	v_exp_f32_e32 v96, v96
	v_exp_f32_e32 v97, v97
	s_nop 0
	v_pk_add_f32 v[96:97], v[96:97], 1.0 op_sel_hi:[1,0]
	s_nop 0
	v_rcp_f32_e32 v96, v96
	v_rcp_f32_e32 v97, v97
	s_nop 0
	v_pk_mul_f32 v[90:91], v[90:91], v[96:97]
	v_pk_mul_f32 v[96:97], v[138:139], v[92:93] op_sel_hi:[1,0]
	v_cvt_pk_bf16_f32 v89, v90, v91
	v_pk_mul_f32 v[84:85], v[84:85], v[96:97]
	s_nop 0
	v_pk_mul_f32 v[96:97], v[84:85], s[6:7] op_sel_hi:[1,0]
	s_nop 0
	v_exp_f32_e32 v96, v96
	v_exp_f32_e32 v97, v97
	s_nop 0
	v_pk_add_f32 v[96:97], v[96:97], 1.0 op_sel_hi:[1,0]
	s_nop 0
	v_rcp_f32_e32 v96, v96
	v_rcp_f32_e32 v97, v97
	s_nop 0
	v_pk_mul_f32 v[84:85], v[84:85], v[96:97]
	v_pk_mul_f32 v[96:97], v[136:137], v[92:93] op_sel_hi:[1,0]
	v_add_u32_e32 v93, 0x90, v133
	v_pk_mul_f32 v[86:87], v[86:87], v[96:97]
	v_cvt_pk_bf16_f32 v90, v84, v85
	v_pk_mul_f32 v[96:97], v[86:87], s[6:7] op_sel_hi:[1,0]
	v_mad_i64_i32 v[84:85], s[0:1], v93, s81, v[128:129]
	v_exp_f32_e32 v96, v96
	v_exp_f32_e32 v97, v97
	s_nop 0
	v_pk_add_f32 v[96:97], v[96:97], 1.0 op_sel_hi:[1,0]
	s_nop 0
	v_rcp_f32_e32 v96, v96
	v_rcp_f32_e32 v97, v97
	s_nop 0
	v_pk_mul_f32 v[86:87], v[86:87], v[96:97]
	s_nop 0
	v_cvt_pk_bf16_f32 v91, v86, v87
	v_lshl_add_u64 v[86:87], v[84:85], 0, v[66:67]
	ds_bpermute_b32 v84, v153, v152 offset:128
	global_store_dwordx4 v[86:87], v[88:91], off
	s_waitcnt lgkmcnt(0)
	s_nop 0
	v_pk_mul_f32 v[88:89], v[150:151], v[84:85] op_sel_hi:[1,0]
	s_nop 0
	v_pk_mul_f32 v[80:81], v[80:81], v[88:89]
	s_nop 0
	v_pk_mul_f32 v[88:89], v[80:81], s[6:7] op_sel_hi:[1,0]
	s_nop 0
	v_exp_f32_e32 v88, v88
	v_exp_f32_e32 v89, v89
	s_nop 0
	v_pk_add_f32 v[88:89], v[88:89], 1.0 op_sel_hi:[1,0]
	s_nop 0
	v_rcp_f32_e32 v88, v88
	v_rcp_f32_e32 v89, v89
	s_nop 0
	v_pk_mul_f32 v[80:81], v[80:81], v[88:89]
	v_pk_mul_f32 v[88:89], v[148:149], v[84:85] op_sel_hi:[1,0]
	v_cvt_pk_bf16_f32 v80, v80, v81
	v_pk_mul_f32 v[82:83], v[82:83], v[88:89]
	s_nop 0
	v_pk_mul_f32 v[88:89], v[82:83], s[6:7] op_sel_hi:[1,0]
	s_nop 0
	v_exp_f32_e32 v88, v88
	v_exp_f32_e32 v89, v89
	s_nop 0
	v_pk_add_f32 v[88:89], v[88:89], 1.0 op_sel_hi:[1,0]
	s_nop 0
	v_rcp_f32_e32 v88, v88
	v_rcp_f32_e32 v89, v89
	s_nop 0
	v_pk_mul_f32 v[82:83], v[82:83], v[88:89]
	v_pk_mul_f32 v[88:89], v[138:139], v[84:85] op_sel_hi:[1,0]
	v_cvt_pk_bf16_f32 v81, v82, v83
	v_pk_mul_f32 v[76:77], v[76:77], v[88:89]
	s_nop 0
	v_pk_mul_f32 v[88:89], v[76:77], s[6:7] op_sel_hi:[1,0]
	s_nop 0
	v_exp_f32_e32 v88, v88
	v_exp_f32_e32 v89, v89
	s_nop 0
	v_pk_add_f32 v[88:89], v[88:89], 1.0 op_sel_hi:[1,0]
	s_nop 0
	v_rcp_f32_e32 v88, v88
	v_rcp_f32_e32 v89, v89
	s_nop 0
	v_pk_mul_f32 v[76:77], v[76:77], v[88:89]
	v_pk_mul_f32 v[88:89], v[136:137], v[84:85] op_sel_hi:[1,0]
	v_add_u32_e32 v85, 0xa0, v133
	v_pk_mul_f32 v[78:79], v[78:79], v[88:89]
	v_cvt_pk_bf16_f32 v82, v76, v77
	v_pk_mul_f32 v[88:89], v[78:79], s[6:7] op_sel_hi:[1,0]
	v_mad_i64_i32 v[76:77], s[0:1], v85, s81, v[128:129]
	v_exp_f32_e32 v88, v88
	v_exp_f32_e32 v89, v89
	s_nop 0
	v_pk_add_f32 v[88:89], v[88:89], 1.0 op_sel_hi:[1,0]
	s_nop 0
	v_rcp_f32_e32 v88, v88
	v_rcp_f32_e32 v89, v89
	s_nop 0
	v_pk_mul_f32 v[78:79], v[78:79], v[88:89]
	s_nop 0
	v_cvt_pk_bf16_f32 v83, v78, v79
	v_lshl_add_u64 v[78:79], v[76:77], 0, v[66:67]
	ds_bpermute_b32 v76, v153, v152 offset:192
	global_store_dwordx4 v[78:79], v[80:83], off
	s_waitcnt lgkmcnt(0)
;     template <int KIND>
;     __device__ __forceinline__ void run(const f32x4 (&acc)[2][2][4][2], const Unit& u, int wr, int wc, int fr, int fq) const {
;         const int row0 = u.pm * BM + wr * 64 + fr, col0 = u.pn * BM + wc * 32 + 8 * fq;
;         const float sa_lo = sa[u.pm * BM + wr * 64 + fr + 16 * fq], sa_hi = sa[u.pm * BM + HALF + wr * 64 + fr + 16 * fq];
; #pragma unroll
;         for (int bj = 0; bj < 2; ++bj) {
;             f32x2_t sc2[4], aux2[4];
; #pragma unroll
;             for (int j = 0; j < 4; ++j) {
;                 const float k0 = (KIND == 4) ? (0.125f * LOG2E / 127.0f) : (1.0f / 127.0f);
;                 sc2[j] = (f32x2_t){wmax[col0 + bj * HALF + 2 * j] * k0, wmax[col0 + bj * HALF + 2 * j + 1] * k0};
;                 if (KIND == 1) aux2[j] = (f32x2_t){lb[col0 - C_HG + bj * HALF + 2 * j], lb[col0 - C_HG + bj * HALF + 2 * j + 1]};
;                 else if (KIND == 3) aux2[j] = (f32x2_t){gain[col0 - C_HGATE + bj * HALF + 2 * j], gain[col0 - C_HGATE + bj * HALF + 2 * j + 1]};
;                 else aux2[j] = (f32x2_t){0.f, 0.f};
;             }
; #pragma unroll
;             for (int ai = 0; ai < 2; ++ai)
; #pragma unroll
;                 for (int m = 0; m < 4; ++m) { const int row = row0 + ai * HALF + m * 16; const float a = __shfl(ai ? sa_hi : sa_lo, 16 * m + fr);
;                     const f32x4 f0 = __builtin_convertvector(__builtin_bit_cast(i32x4, acc[ai][bj][m][0]), f32x4), f1 = __builtin_convertvector(__builtin_bit_cast(i32x4, acc[ai][bj][m][1]), f32x4);
;                     f32x2_t v[4] = {(f32x2_t){f0[0], f0[1]}, (f32x2_t){f0[2], f0[3]}, (f32x2_t){f1[0], f1[1]}, (f32x2_t){f1[2], f1[3]}};
; #pragma unroll
;                     for (int j = 0; j < 4; ++j) {
;                         v[j] = v[j] * (sc2[j] * (f32x2_t){a, a});
;                         if (KIND == 0 || KIND == 1 || KIND == 3) {
;                             const f32x2_t e = v[j] * (f32x2_t){-LOG2E, -LOG2E};
;                             const f32x2_t dn = (f32x2_t){__builtin_amdgcn_exp2f(e[0]), __builtin_amdgcn_exp2f(e[1])} + (f32x2_t){1.0f, 1.0f};
;                             const f32x2_t sg = (f32x2_t){fast_rcp(dn[0]), fast_rcp(dn[1])};
;                             if (KIND == 0) v[j] = v[j] * sg;
;                             else if (KIND == 3) v[j] = (v[j] * sg) * aux2[j];
	s_nop 0
	v_pk_mul_f32 v[80:81], v[150:151], v[76:77] op_sel_hi:[1,0]
	s_nop 0
	v_pk_mul_f32 v[72:73], v[72:73], v[80:81]
	s_nop 0
	v_pk_mul_f32 v[80:81], v[72:73], s[6:7] op_sel_hi:[1,0]
	s_nop 0
	v_exp_f32_e32 v80, v80
	v_exp_f32_e32 v81, v81
	s_nop 0
	v_pk_add_f32 v[80:81], v[80:81], 1.0 op_sel_hi:[1,0]
	s_nop 0
	v_rcp_f32_e32 v80, v80
	v_rcp_f32_e32 v81, v81
	s_nop 0
	v_pk_mul_f32 v[72:73], v[72:73], v[80:81]
	v_pk_mul_f32 v[80:81], v[148:149], v[76:77] op_sel_hi:[1,0]
	s_nop 0
	v_pk_mul_f32 v[74:75], v[74:75], v[80:81]
	s_nop 0
	v_pk_mul_f32 v[80:81], v[74:75], s[6:7] op_sel_hi:[1,0]
	s_nop 0
	v_exp_f32_e32 v80, v80
	v_exp_f32_e32 v81, v81
	s_nop 0
	v_pk_add_f32 v[80:81], v[80:81], 1.0 op_sel_hi:[1,0]
	s_nop 0
	v_rcp_f32_e32 v80, v80
	v_rcp_f32_e32 v81, v81
	s_nop 0
	v_pk_mul_f32 v[74:75], v[74:75], v[80:81]
	v_pk_mul_f32 v[80:81], v[138:139], v[76:77] op_sel_hi:[1,0]
	s_nop 0
	v_pk_mul_f32 v[68:69], v[68:69], v[80:81]
	s_nop 0
	v_pk_mul_f32 v[80:81], v[68:69], s[6:7] op_sel_hi:[1,0]
	s_nop 0
	v_exp_f32_e32 v80, v80
	v_exp_f32_e32 v81, v81
	s_nop 0
	v_pk_add_f32 v[80:81], v[80:81], 1.0 op_sel_hi:[1,0]
	s_nop 0
	v_rcp_f32_e32 v80, v80
	v_rcp_f32_e32 v81, v81
	s_nop 0
	v_pk_mul_f32 v[80:81], v[68:69], v[80:81]
	v_pk_mul_f32 v[68:69], v[136:137], v[76:77] op_sel_hi:[1,0]
	v_add_u32_e32 v77, 0xb0, v133
	v_pk_mul_f32 v[68:69], v[70:71], v[68:69]
	v_mad_i64_i32 v[150:151], s[0:1], v77, s81, 0
	v_pk_mul_f32 v[70:71], v[68:69], s[6:7] op_sel_hi:[1,0]
	s_nop 0
	v_exp_f32_e32 v70, v70
	v_exp_f32_e32 v71, v71
	s_nop 0
	v_pk_add_f32 v[70:71], v[70:71], 1.0 op_sel_hi:[1,0]
	s_nop 0
	v_rcp_f32_e32 v70, v70
	v_rcp_f32_e32 v71, v71
	s_nop 0
	v_pk_mul_f32 v[82:83], v[68:69], v[70:71]
	v_cvt_pk_bf16_f32 v68, v72, v73
	v_mad_i64_i32 v[72:73], s[0:1], v77, s81, v[128:129]
	v_cvt_pk_bf16_f32 v69, v74, v75
	v_cvt_pk_bf16_f32 v70, v80, v81
	v_cvt_pk_bf16_f32 v71, v82, v83
	v_lshl_add_u64 v[72:73], v[72:73], 0, v[66:67]
	global_store_dwordx4 v[72:73], v[68:71], off
	s_nop 1
	v_mov_b32_e32 v80, v236
	v_mov_b32_e32 v81, v237
	v_mov_b32_e32 v82, v238
	v_mov_b32_e32 v83, v239
	v_mov_b32_e32 v68, v240
	v_mov_b32_e32 v69, v241
	v_mov_b32_e32 v70, v242
	v_mov_b32_e32 v71, v243
	v_pk_mul_f32 v[74:75], v[68:69], s[2:3] op_sel_hi:[1,0]
	v_pk_mul_f32 v[72:73], v[70:71], s[2:3] op_sel_hi:[1,0]
	v_pk_mul_f32 v[70:71], v[80:81], s[2:3] op_sel_hi:[1,0]
	v_pk_mul_f32 v[80:81], v[132:133], v[74:75] op_sel_hi:[0,1]
	v_pk_mul_f32 v[62:63], v[62:63], v[80:81]
	v_pk_mul_f32 v[68:69], v[82:83], s[2:3] op_sel_hi:[1,0]
	v_pk_mul_f32 v[80:81], v[62:63], s[6:7] op_sel_hi:[1,0]
	s_nop 0
	v_exp_f32_e32 v80, v80
	v_exp_f32_e32 v81, v81
	s_nop 0
	v_pk_add_f32 v[80:81], v[80:81], 1.0 op_sel_hi:[1,0]
	s_nop 0
	v_rcp_f32_e32 v80, v80
	v_rcp_f32_e32 v81, v81
	s_nop 0
	v_pk_mul_f32 v[62:63], v[62:63], v[80:81]
	v_pk_mul_f32 v[80:81], v[132:133], v[72:73] op_sel_hi:[0,1]
	v_pk_mul_f32 v[64:65], v[64:65], v[80:81]
	s_nop 0
	v_pk_mul_f32 v[80:81], v[64:65], s[6:7] op_sel_hi:[1,0]
	s_nop 0
	v_exp_f32_e32 v80, v80
	v_exp_f32_e32 v81, v81
	s_nop 0
	v_pk_add_f32 v[80:81], v[80:81], 1.0 op_sel_hi:[1,0]
	s_nop 0
	v_rcp_f32_e32 v80, v80
	v_rcp_f32_e32 v81, v81
	s_nop 0
	v_pk_mul_f32 v[64:65], v[64:65], v[80:81]
	v_pk_mul_f32 v[80:81], v[132:133], v[70:71] op_sel_hi:[0,1]
	v_pk_mul_f32 v[58:59], v[58:59], v[80:81]
	s_nop 0
	v_pk_mul_f32 v[80:81], v[58:59], s[6:7] op_sel_hi:[1,0]
	s_nop 0
	v_exp_f32_e32 v80, v80
	v_exp_f32_e32 v81, v81
	s_nop 0
	v_pk_add_f32 v[80:81], v[80:81], 1.0 op_sel_hi:[1,0]
	s_nop 0
	v_rcp_f32_e32 v80, v80
	v_rcp_f32_e32 v81, v81
	s_nop 0
	v_pk_mul_f32 v[80:81], v[58:59], v[80:81]
	v_pk_mul_f32 v[58:59], v[132:133], v[68:69] op_sel_hi:[0,1]
	v_pk_mul_f32 v[58:59], v[60:61], v[58:59]
	s_nop 0
	v_pk_mul_f32 v[60:61], v[58:59], s[6:7] op_sel_hi:[1,0]
	s_nop 0
	v_exp_f32_e32 v60, v60
	v_exp_f32_e32 v61, v61
	s_nop 0
	v_pk_add_f32 v[60:61], v[60:61], 1.0 op_sel_hi:[1,0]
	s_nop 0
	v_rcp_f32_e32 v60, v60
	v_rcp_f32_e32 v61, v61
	s_nop 0
	v_pk_mul_f32 v[82:83], v[58:59], v[60:61]
	v_cvt_pk_bf16_f32 v58, v62, v63
	v_cvt_pk_bf16_f32 v59, v64, v65
	v_cvt_pk_bf16_f32 v60, v80, v81
	v_cvt_pk_bf16_f32 v61, v82, v83
	global_store_dwordx4 v[126:127], v[58:61], off offset:256
	s_nop 1
	v_pk_mul_f32 v[58:59], v[124:125], v[74:75] op_sel_hi:[0,1]
	v_pk_mul_f32 v[54:55], v[54:55], v[58:59]
	s_nop 0
	v_pk_mul_f32 v[58:59], v[54:55], s[6:7] op_sel_hi:[1,0]
	s_nop 0
	v_exp_f32_e32 v58, v58
	v_exp_f32_e32 v59, v59
	s_nop 0
	v_pk_add_f32 v[58:59], v[58:59], 1.0 op_sel_hi:[1,0]
	s_nop 0
	v_rcp_f32_e32 v58, v58
	v_rcp_f32_e32 v59, v59
	s_nop 0
	v_pk_mul_f32 v[54:55], v[54:55], v[58:59]
	v_pk_mul_f32 v[58:59], v[124:125], v[72:73] op_sel_hi:[0,1]
	v_pk_mul_f32 v[56:57], v[56:57], v[58:59]
	s_nop 0
	v_pk_mul_f32 v[58:59], v[56:57], s[6:7] op_sel_hi:[1,0]
	s_nop 0
	v_exp_f32_e32 v58, v58
	v_exp_f32_e32 v59, v59
	s_nop 0
	v_pk_add_f32 v[58:59], v[58:59], 1.0 op_sel_hi:[1,0]
	s_nop 0
	v_rcp_f32_e32 v58, v58
	v_rcp_f32_e32 v59, v59
	s_nop 0
	v_pk_mul_f32 v[56:57], v[56:57], v[58:59]
	v_pk_mul_f32 v[58:59], v[124:125], v[70:71] op_sel_hi:[0,1]
	v_pk_mul_f32 v[50:51], v[50:51], v[58:59]
	s_nop 0
	v_pk_mul_f32 v[58:59], v[50:51], s[6:7] op_sel_hi:[1,0]
	s_nop 0
	v_exp_f32_e32 v58, v58
	v_exp_f32_e32 v59, v59
	s_nop 0
	v_pk_add_f32 v[58:59], v[58:59], 1.0 op_sel_hi:[1,0]
	s_nop 0
	v_rcp_f32_e32 v58, v58
	v_rcp_f32_e32 v59, v59
	s_nop 0
	v_pk_mul_f32 v[58:59], v[50:51], v[58:59]
	v_pk_mul_f32 v[50:51], v[124:125], v[68:69] op_sel_hi:[0,1]
	v_pk_mul_f32 v[50:51], v[52:53], v[50:51]
	s_nop 0
	v_pk_mul_f32 v[52:53], v[50:51], s[6:7] op_sel_hi:[1,0]
	s_nop 0
	v_exp_f32_e32 v52, v52
	v_exp_f32_e32 v53, v53
	s_nop 0
;     template <int KIND>
;     __device__ __forceinline__ void run(const f32x4 (&acc)[2][2][4][2], const Unit& u, int wr, int wc, int fr, int fq) const {
;         const int row0 = u.pm * BM + wr * 64 + fr, col0 = u.pn * BM + wc * 32 + 8 * fq;
;         const float sa_lo = sa[u.pm * BM + wr * 64 + fr + 16 * fq], sa_hi = sa[u.pm * BM + HALF + wr * 64 + fr + 16 * fq];
; #pragma unroll
;         for (int bj = 0; bj < 2; ++bj) {
;             f32x2_t sc2[4], aux2[4];
; #pragma unroll
;             for (int j = 0; j < 4; ++j) {
;                 const float k0 = (KIND == 4) ? (0.125f * LOG2E / 127.0f) : (1.0f / 127.0f);
;                 sc2[j] = (f32x2_t){wmax[col0 + bj * HALF + 2 * j] * k0, wmax[col0 + bj * HALF + 2 * j + 1] * k0};
;                 if (KIND == 1) aux2[j] = (f32x2_t){lb[col0 - C_HG + bj * HALF + 2 * j], lb[col0 - C_HG + bj * HALF + 2 * j + 1]};
;                 else if (KIND == 3) aux2[j] = (f32x2_t){gain[col0 - C_HGATE + bj * HALF + 2 * j], gain[col0 - C_HGATE + bj * HALF + 2 * j + 1]};
;                 else aux2[j] = (f32x2_t){0.f, 0.f};
;             }
; #pragma unroll
;             for (int ai = 0; ai < 2; ++ai)
; #pragma unroll
;                 for (int m = 0; m < 4; ++m) { const int row = row0 + ai * HALF + m * 16; const float a = __shfl(ai ? sa_hi : sa_lo, 16 * m + fr);
;                     const f32x4 f0 = __builtin_convertvector(__builtin_bit_cast(i32x4, acc[ai][bj][m][0]), f32x4), f1 = __builtin_convertvector(__builtin_bit_cast(i32x4, acc[ai][bj][m][1]), f32x4);
;                     f32x2_t v[4] = {(f32x2_t){f0[0], f0[1]}, (f32x2_t){f0[2], f0[3]}, (f32x2_t){f1[0], f1[1]}, (f32x2_t){f1[2], f1[3]}};
; #pragma unroll
;                     for (int j = 0; j < 4; ++j) {
;                         v[j] = v[j] * (sc2[j] * (f32x2_t){a, a});
;                         if (KIND == 0 || KIND == 1 || KIND == 3) {
;                             const f32x2_t e = v[j] * (f32x2_t){-LOG2E, -LOG2E};
;                             const f32x2_t dn = (f32x2_t){__builtin_amdgcn_exp2f(e[0]), __builtin_amdgcn_exp2f(e[1])} + (f32x2_t){1.0f, 1.0f};
;                             const f32x2_t sg = (f32x2_t){fast_rcp(dn[0]), fast_rcp(dn[1])};
;                             if (KIND == 0) v[j] = v[j] * sg;
;                             else if (KIND == 3) v[j] = (v[j] * sg) * aux2[j];
	v_pk_add_f32 v[52:53], v[52:53], 1.0 op_sel_hi:[1,0]
	s_nop 0
	v_rcp_f32_e32 v52, v52
	v_rcp_f32_e32 v53, v53
	s_nop 0
	v_pk_mul_f32 v[60:61], v[50:51], v[52:53]
	v_cvt_pk_bf16_f32 v50, v54, v55
	v_cvt_pk_bf16_f32 v51, v56, v57
	v_cvt_pk_bf16_f32 v52, v58, v59
	v_cvt_pk_bf16_f32 v53, v60, v61
	global_store_dwordx4 v[118:119], v[50:53], off offset:256
	s_nop 1
	v_pk_mul_f32 v[50:51], v[116:117], v[74:75] op_sel_hi:[0,1]
	v_pk_mul_f32 v[46:47], v[46:47], v[50:51]
	s_nop 0
	v_pk_mul_f32 v[50:51], v[46:47], s[6:7] op_sel_hi:[1,0]
	s_nop 0
	v_exp_f32_e32 v50, v50
	v_exp_f32_e32 v51, v51
	s_nop 0
	v_pk_add_f32 v[50:51], v[50:51], 1.0 op_sel_hi:[1,0]
	s_nop 0
	v_rcp_f32_e32 v50, v50
	v_rcp_f32_e32 v51, v51
	s_nop 0
	v_pk_mul_f32 v[46:47], v[46:47], v[50:51]
	v_pk_mul_f32 v[50:51], v[116:117], v[72:73] op_sel_hi:[0,1]
	v_pk_mul_f32 v[48:49], v[48:49], v[50:51]
	s_nop 0
	v_pk_mul_f32 v[50:51], v[48:49], s[6:7] op_sel_hi:[1,0]
	s_nop 0
	v_exp_f32_e32 v50, v50
	v_exp_f32_e32 v51, v51
	s_nop 0
	v_pk_add_f32 v[50:51], v[50:51], 1.0 op_sel_hi:[1,0]
	s_nop 0
	v_rcp_f32_e32 v50, v50
	v_rcp_f32_e32 v51, v51
	s_nop 0
	v_pk_mul_f32 v[48:49], v[48:49], v[50:51]
	v_pk_mul_f32 v[50:51], v[116:117], v[70:71] op_sel_hi:[0,1]
	v_pk_mul_f32 v[42:43], v[42:43], v[50:51]
	s_nop 0
	v_pk_mul_f32 v[50:51], v[42:43], s[6:7] op_sel_hi:[1,0]
	s_nop 0
	v_exp_f32_e32 v50, v50
	v_exp_f32_e32 v51, v51
	s_nop 0
	v_pk_add_f32 v[50:51], v[50:51], 1.0 op_sel_hi:[1,0]
	s_nop 0
	v_rcp_f32_e32 v50, v50
	v_rcp_f32_e32 v51, v51
	s_nop 0
	v_pk_mul_f32 v[50:51], v[42:43], v[50:51]
	v_pk_mul_f32 v[42:43], v[116:117], v[68:69] op_sel_hi:[0,1]
	v_pk_mul_f32 v[42:43], v[44:45], v[42:43]
	s_nop 0
	v_pk_mul_f32 v[44:45], v[42:43], s[6:7] op_sel_hi:[1,0]
	s_nop 0
	v_exp_f32_e32 v44, v44
	v_exp_f32_e32 v45, v45
	s_nop 0
	v_pk_add_f32 v[44:45], v[44:45], 1.0 op_sel_hi:[1,0]
	s_nop 0
	v_rcp_f32_e32 v44, v44
	v_rcp_f32_e32 v45, v45
	s_nop 0
	v_pk_mul_f32 v[52:53], v[42:43], v[44:45]
	v_cvt_pk_bf16_f32 v42, v46, v47
	v_cvt_pk_bf16_f32 v43, v48, v49
	v_cvt_pk_bf16_f32 v44, v50, v51
	v_cvt_pk_bf16_f32 v45, v52, v53
	global_store_dwordx4 v[110:111], v[42:45], off offset:256
	s_nop 1
	v_pk_mul_f32 v[42:43], v[108:109], v[74:75] op_sel_hi:[0,1]
	v_pk_mul_f32 v[38:39], v[38:39], v[42:43]
	s_nop 0
	v_pk_mul_f32 v[42:43], v[38:39], s[6:7] op_sel_hi:[1,0]
	s_nop 0
	v_exp_f32_e32 v42, v42
	v_exp_f32_e32 v43, v43
	s_nop 0
	v_pk_add_f32 v[42:43], v[42:43], 1.0 op_sel_hi:[1,0]
	s_nop 0
	v_rcp_f32_e32 v42, v42
	v_rcp_f32_e32 v43, v43
	s_nop 0
	v_pk_mul_f32 v[38:39], v[38:39], v[42:43]
	v_pk_mul_f32 v[42:43], v[108:109], v[72:73] op_sel_hi:[0,1]
	v_pk_mul_f32 v[40:41], v[40:41], v[42:43]
	s_nop 0
	v_pk_mul_f32 v[42:43], v[40:41], s[6:7] op_sel_hi:[1,0]
	s_nop 0
	v_exp_f32_e32 v42, v42
	v_exp_f32_e32 v43, v43
	s_nop 0
	v_pk_add_f32 v[42:43], v[42:43], 1.0 op_sel_hi:[1,0]
	s_nop 0
	v_rcp_f32_e32 v42, v42
	v_rcp_f32_e32 v43, v43
	s_nop 0
	v_pk_mul_f32 v[40:41], v[40:41], v[42:43]
	v_pk_mul_f32 v[42:43], v[108:109], v[70:71] op_sel_hi:[0,1]
	v_pk_mul_f32 v[34:35], v[34:35], v[42:43]
	s_nop 0
	v_pk_mul_f32 v[42:43], v[34:35], s[6:7] op_sel_hi:[1,0]
	s_nop 0
	v_exp_f32_e32 v42, v42
	v_exp_f32_e32 v43, v43
	s_nop 0
	v_pk_add_f32 v[42:43], v[42:43], 1.0 op_sel_hi:[1,0]
	s_nop 0
	v_rcp_f32_e32 v42, v42
	v_rcp_f32_e32 v43, v43
	s_nop 0
	v_pk_mul_f32 v[42:43], v[34:35], v[42:43]
	v_pk_mul_f32 v[34:35], v[108:109], v[68:69] op_sel_hi:[0,1]
	v_pk_mul_f32 v[34:35], v[36:37], v[34:35]
	s_nop 0
	v_pk_mul_f32 v[36:37], v[34:35], s[6:7] op_sel_hi:[1,0]
	s_nop 0
	v_exp_f32_e32 v36, v36
	v_exp_f32_e32 v37, v37
	s_nop 0
	v_pk_add_f32 v[36:37], v[36:37], 1.0 op_sel_hi:[1,0]
	s_nop 0
	v_rcp_f32_e32 v36, v36
	v_rcp_f32_e32 v37, v37
	s_nop 0
	v_pk_mul_f32 v[44:45], v[34:35], v[36:37]
	v_cvt_pk_bf16_f32 v34, v38, v39
	v_cvt_pk_bf16_f32 v35, v40, v41
	v_cvt_pk_bf16_f32 v36, v42, v43
	v_cvt_pk_bf16_f32 v37, v44, v45
	global_store_dwordx4 v[102:103], v[34:37], off offset:256
	s_nop 1
	v_pk_mul_f32 v[34:35], v[100:101], v[74:75] op_sel_hi:[0,1]
	v_pk_mul_f32 v[30:31], v[30:31], v[34:35]
	s_nop 0
	v_pk_mul_f32 v[34:35], v[30:31], s[6:7] op_sel_hi:[1,0]
	s_nop 0
	v_exp_f32_e32 v34, v34
	v_exp_f32_e32 v35, v35
	s_nop 0
	v_pk_add_f32 v[34:35], v[34:35], 1.0 op_sel_hi:[1,0]
	s_nop 0
	v_rcp_f32_e32 v34, v34
	v_rcp_f32_e32 v35, v35
	s_nop 0
	v_pk_mul_f32 v[30:31], v[30:31], v[34:35]
	v_pk_mul_f32 v[34:35], v[100:101], v[72:73] op_sel_hi:[0,1]
	v_pk_mul_f32 v[32:33], v[32:33], v[34:35]
	s_nop 0
	v_pk_mul_f32 v[34:35], v[32:33], s[6:7] op_sel_hi:[1,0]
	s_nop 0
	v_exp_f32_e32 v34, v34
	v_exp_f32_e32 v35, v35
	s_nop 0
	v_pk_add_f32 v[34:35], v[34:35], 1.0 op_sel_hi:[1,0]
	s_nop 0
	v_rcp_f32_e32 v34, v34
	v_rcp_f32_e32 v35, v35
	s_nop 0
	v_pk_mul_f32 v[32:33], v[32:33], v[34:35]
	v_pk_mul_f32 v[34:35], v[100:101], v[70:71] op_sel_hi:[0,1]
	v_pk_mul_f32 v[26:27], v[26:27], v[34:35]
	s_nop 0
	v_pk_mul_f32 v[34:35], v[26:27], s[6:7] op_sel_hi:[1,0]
	s_nop 0
	v_exp_f32_e32 v34, v34
	v_exp_f32_e32 v35, v35
	s_nop 0
	v_pk_add_f32 v[34:35], v[34:35], 1.0 op_sel_hi:[1,0]
	s_nop 0
	v_rcp_f32_e32 v34, v34
	v_rcp_f32_e32 v35, v35
	s_nop 0
	v_pk_mul_f32 v[34:35], v[26:27], v[34:35]
	v_pk_mul_f32 v[26:27], v[100:101], v[68:69] op_sel_hi:[0,1]
	v_pk_mul_f32 v[26:27], v[28:29], v[26:27]
	s_nop 0
	v_pk_mul_f32 v[28:29], v[26:27], s[6:7] op_sel_hi:[1,0]
	s_nop 0
	v_exp_f32_e32 v28, v28
	v_exp_f32_e32 v29, v29
	s_nop 0
;     template <int KIND>
;     __device__ __forceinline__ void run(const f32x4 (&acc)[2][2][4][2], const Unit& u, int wr, int wc, int fr, int fq) const {
;         const int row0 = u.pm * BM + wr * 64 + fr, col0 = u.pn * BM + wc * 32 + 8 * fq;
;         const float sa_lo = sa[u.pm * BM + wr * 64 + fr + 16 * fq], sa_hi = sa[u.pm * BM + HALF + wr * 64 + fr + 16 * fq];
; #pragma unroll
;         for (int bj = 0; bj < 2; ++bj) {
;             f32x2_t sc2[4], aux2[4];
; #pragma unroll
;             for (int j = 0; j < 4; ++j) {
;                 const float k0 = (KIND == 4) ? (0.125f * LOG2E / 127.0f) : (1.0f / 127.0f);
;                 sc2[j] = (f32x2_t){wmax[col0 + bj * HALF + 2 * j] * k0, wmax[col0 + bj * HALF + 2 * j + 1] * k0};
;                 if (KIND == 1) aux2[j] = (f32x2_t){lb[col0 - C_HG + bj * HALF + 2 * j], lb[col0 - C_HG + bj * HALF + 2 * j + 1]};
;                 else if (KIND == 3) aux2[j] = (f32x2_t){gain[col0 - C_HGATE + bj * HALF + 2 * j], gain[col0 - C_HGATE + bj * HALF + 2 * j + 1]};
;                 else aux2[j] = (f32x2_t){0.f, 0.f};
;             }
; #pragma unroll
;             for (int ai = 0; ai < 2; ++ai)
; #pragma unroll
;                 for (int m = 0; m < 4; ++m) { const int row = row0 + ai * HALF + m * 16; const float a = __shfl(ai ? sa_hi : sa_lo, 16 * m + fr);
;                     const f32x4 f0 = __builtin_convertvector(__builtin_bit_cast(i32x4, acc[ai][bj][m][0]), f32x4), f1 = __builtin_convertvector(__builtin_bit_cast(i32x4, acc[ai][bj][m][1]), f32x4);
;                     f32x2_t v[4] = {(f32x2_t){f0[0], f0[1]}, (f32x2_t){f0[2], f0[3]}, (f32x2_t){f1[0], f1[1]}, (f32x2_t){f1[2], f1[3]}};
; #pragma unroll
;                     for (int j = 0; j < 4; ++j) {
;                         v[j] = v[j] * (sc2[j] * (f32x2_t){a, a});
;                         if (KIND == 0 || KIND == 1 || KIND == 3) {
;                             const f32x2_t e = v[j] * (f32x2_t){-LOG2E, -LOG2E};
;                             const f32x2_t dn = (f32x2_t){__builtin_amdgcn_exp2f(e[0]), __builtin_amdgcn_exp2f(e[1])} + (f32x2_t){1.0f, 1.0f};
;                             const f32x2_t sg = (f32x2_t){fast_rcp(dn[0]), fast_rcp(dn[1])};
;                             if (KIND == 0) v[j] = v[j] * sg;
;                             else if (KIND == 3) v[j] = (v[j] * sg) * aux2[j];
	v_pk_add_f32 v[28:29], v[28:29], 1.0 op_sel_hi:[1,0]
	s_nop 0
	v_rcp_f32_e32 v28, v28
	v_rcp_f32_e32 v29, v29
	s_nop 0
	v_pk_mul_f32 v[36:37], v[26:27], v[28:29]
	v_cvt_pk_bf16_f32 v26, v30, v31
	v_cvt_pk_bf16_f32 v27, v32, v33
	v_cvt_pk_bf16_f32 v28, v34, v35
	v_cvt_pk_bf16_f32 v29, v36, v37
	global_store_dwordx4 v[94:95], v[26:29], off offset:256
	s_nop 1
	v_pk_mul_f32 v[26:27], v[92:93], v[74:75] op_sel_hi:[0,1]
	v_pk_mul_f32 v[22:23], v[22:23], v[26:27]
	s_nop 0
	v_pk_mul_f32 v[26:27], v[22:23], s[6:7] op_sel_hi:[1,0]
	s_nop 0
	v_exp_f32_e32 v26, v26
	v_exp_f32_e32 v27, v27
	s_nop 0
	v_pk_add_f32 v[26:27], v[26:27], 1.0 op_sel_hi:[1,0]
	s_nop 0
	v_rcp_f32_e32 v26, v26
	v_rcp_f32_e32 v27, v27
	s_nop 0
	v_pk_mul_f32 v[22:23], v[22:23], v[26:27]
	v_pk_mul_f32 v[26:27], v[92:93], v[72:73] op_sel_hi:[0,1]
	v_pk_mul_f32 v[24:25], v[24:25], v[26:27]
	s_nop 0
	v_pk_mul_f32 v[26:27], v[24:25], s[6:7] op_sel_hi:[1,0]
	s_nop 0
	v_exp_f32_e32 v26, v26
	v_exp_f32_e32 v27, v27
	s_nop 0
	v_pk_add_f32 v[26:27], v[26:27], 1.0 op_sel_hi:[1,0]
	s_nop 0
	v_rcp_f32_e32 v26, v26
	v_rcp_f32_e32 v27, v27
	s_nop 0
	v_pk_mul_f32 v[24:25], v[24:25], v[26:27]
	v_pk_mul_f32 v[26:27], v[92:93], v[70:71] op_sel_hi:[0,1]
	v_pk_mul_f32 v[18:19], v[18:19], v[26:27]
	s_nop 0
	v_pk_mul_f32 v[26:27], v[18:19], s[6:7] op_sel_hi:[1,0]
	s_nop 0
	v_exp_f32_e32 v26, v26
	v_exp_f32_e32 v27, v27
	s_nop 0
	v_pk_add_f32 v[26:27], v[26:27], 1.0 op_sel_hi:[1,0]
	s_nop 0
	v_rcp_f32_e32 v26, v26
	v_rcp_f32_e32 v27, v27
	s_nop 0
	v_pk_mul_f32 v[26:27], v[18:19], v[26:27]
	v_pk_mul_f32 v[18:19], v[92:93], v[68:69] op_sel_hi:[0,1]
	v_pk_mul_f32 v[18:19], v[20:21], v[18:19]
	s_nop 0
	v_pk_mul_f32 v[20:21], v[18:19], s[6:7] op_sel_hi:[1,0]
	s_nop 0
	v_exp_f32_e32 v20, v20
	v_exp_f32_e32 v21, v21
	s_nop 0
	v_pk_add_f32 v[20:21], v[20:21], 1.0 op_sel_hi:[1,0]
	s_nop 0
	v_rcp_f32_e32 v20, v20
	v_rcp_f32_e32 v21, v21
	s_nop 0
	v_pk_mul_f32 v[28:29], v[18:19], v[20:21]
	v_cvt_pk_bf16_f32 v18, v22, v23
	v_cvt_pk_bf16_f32 v19, v24, v25
	v_cvt_pk_bf16_f32 v20, v26, v27
	v_cvt_pk_bf16_f32 v21, v28, v29
	global_store_dwordx4 v[86:87], v[18:21], off offset:256
	s_nop 1
	v_pk_mul_f32 v[18:19], v[84:85], v[74:75] op_sel_hi:[0,1]
	v_pk_mul_f32 v[14:15], v[14:15], v[18:19]
	s_nop 0
	v_pk_mul_f32 v[18:19], v[14:15], s[6:7] op_sel_hi:[1,0]
	s_nop 0
	v_exp_f32_e32 v18, v18
	v_exp_f32_e32 v19, v19
	s_nop 0
	v_pk_add_f32 v[18:19], v[18:19], 1.0 op_sel_hi:[1,0]
	s_nop 0
	v_rcp_f32_e32 v18, v18
	v_rcp_f32_e32 v19, v19
	s_nop 0
	v_pk_mul_f32 v[14:15], v[14:15], v[18:19]
	v_pk_mul_f32 v[18:19], v[84:85], v[72:73] op_sel_hi:[0,1]
	v_pk_mul_f32 v[16:17], v[16:17], v[18:19]
	s_nop 0
	v_pk_mul_f32 v[18:19], v[16:17], s[6:7] op_sel_hi:[1,0]
	s_nop 0
	v_exp_f32_e32 v18, v18
	v_exp_f32_e32 v19, v19
	s_nop 0
	v_pk_add_f32 v[18:19], v[18:19], 1.0 op_sel_hi:[1,0]
	s_nop 0
	v_rcp_f32_e32 v18, v18
	v_rcp_f32_e32 v19, v19
	s_nop 0
	v_pk_mul_f32 v[16:17], v[16:17], v[18:19]
	v_pk_mul_f32 v[18:19], v[84:85], v[70:71] op_sel_hi:[0,1]
	v_pk_mul_f32 v[10:11], v[10:11], v[18:19]
	s_nop 0
	v_pk_mul_f32 v[18:19], v[10:11], s[6:7] op_sel_hi:[1,0]
	s_nop 0
	v_exp_f32_e32 v18, v18
	v_exp_f32_e32 v19, v19
	s_nop 0
	v_pk_add_f32 v[18:19], v[18:19], 1.0 op_sel_hi:[1,0]
	s_nop 0
	v_rcp_f32_e32 v18, v18
	v_rcp_f32_e32 v19, v19
	s_nop 0
	v_pk_mul_f32 v[18:19], v[10:11], v[18:19]
	v_pk_mul_f32 v[10:11], v[84:85], v[68:69] op_sel_hi:[0,1]
	v_pk_mul_f32 v[10:11], v[12:13], v[10:11]
	s_nop 0
	v_pk_mul_f32 v[12:13], v[10:11], s[6:7] op_sel_hi:[1,0]
	s_nop 0
	v_exp_f32_e32 v12, v12
	v_exp_f32_e32 v13, v13
	s_nop 0
	v_pk_add_f32 v[12:13], v[12:13], 1.0 op_sel_hi:[1,0]
	s_nop 0
	v_rcp_f32_e32 v12, v12
	v_rcp_f32_e32 v13, v13
	s_nop 0
	v_pk_mul_f32 v[20:21], v[10:11], v[12:13]
	v_cvt_pk_bf16_f32 v10, v14, v15
	v_cvt_pk_bf16_f32 v11, v16, v17
	v_cvt_pk_bf16_f32 v12, v18, v19
	v_cvt_pk_bf16_f32 v13, v20, v21
	global_store_dwordx4 v[78:79], v[10:13], off offset:256
	s_nop 1
	v_pk_mul_f32 v[10:11], v[76:77], v[74:75] op_sel_hi:[0,1]
	v_pk_mul_f32 v[6:7], v[6:7], v[10:11]
	s_nop 0
	v_pk_mul_f32 v[10:11], v[6:7], s[6:7] op_sel_hi:[1,0]
	s_nop 0
	v_exp_f32_e32 v10, v10
	v_exp_f32_e32 v11, v11
	s_nop 0
	v_pk_add_f32 v[10:11], v[10:11], 1.0 op_sel_hi:[1,0]
	s_nop 0
	v_rcp_f32_e32 v10, v10
	v_rcp_f32_e32 v11, v11
	s_nop 0
	v_pk_mul_f32 v[136:137], v[6:7], v[10:11]
	v_pk_mul_f32 v[6:7], v[76:77], v[72:73] op_sel_hi:[0,1]
	v_pk_mul_f32 v[6:7], v[8:9], v[6:7]
	s_nop 0
	v_pk_mul_f32 v[8:9], v[6:7], s[6:7] op_sel_hi:[1,0]
	s_nop 0
	v_exp_f32_e32 v8, v8
	v_exp_f32_e32 v9, v9
	s_nop 0
	v_pk_add_f32 v[8:9], v[8:9], 1.0 op_sel_hi:[1,0]
	s_nop 0
	v_rcp_f32_e32 v8, v8
	v_rcp_f32_e32 v9, v9
	s_nop 0
	v_pk_mul_f32 v[138:139], v[6:7], v[8:9]
	v_pk_mul_f32 v[6:7], v[76:77], v[70:71] op_sel_hi:[0,1]
	v_pk_mul_f32 v[2:3], v[2:3], v[6:7]
	s_nop 0
	v_pk_mul_f32 v[6:7], v[2:3], s[6:7] op_sel_hi:[1,0]
	s_nop 0
	v_exp_f32_e32 v6, v6
	v_exp_f32_e32 v7, v7
	s_nop 0
	v_pk_add_f32 v[6:7], v[6:7], 1.0 op_sel_hi:[1,0]
	s_nop 0
	v_rcp_f32_e32 v6, v6
	v_rcp_f32_e32 v7, v7
	s_nop 0
	v_pk_mul_f32 v[132:133], v[2:3], v[6:7]
	v_pk_mul_f32 v[2:3], v[76:77], v[68:69] op_sel_hi:[0,1]
	v_pk_mul_f32 v[2:3], v[4:5], v[2:3]
	s_nop 0
	v_pk_mul_f32 v[4:5], v[2:3], s[6:7] op_sel_hi:[1,0]
	s_nop 0
	v_exp_f32_e32 v4, v4
	v_exp_f32_e32 v5, v5
	s_nop 0
	v_pk_add_f32 v[4:5], v[4:5], 1.0 op_sel_hi:[1,0]
	s_nop 0
	v_rcp_f32_e32 v4, v4
	v_rcp_f32_e32 v5, v5
	s_nop 0
	v_pk_mul_f32 v[134:135], v[2:3], v[4:5]

;     template <int KIND>
;     __device__ __forceinline__ void run(const f32x4 (&acc)[2][2][4][2], const Unit& u, int wr, int wc, int fr, int fq) const {
;         const int row0 = u.pm * BM + wr * 64 + fr, col0 = u.pn * BM + wc * 32 + 8 * fq;
;         const float sa_lo = sa[u.pm * BM + wr * 64 + fr + 16 * fq], sa_hi = sa[u.pm * BM + HALF + wr * 64 + fr + 16 * fq];
; #pragma unroll
;         for (int bj = 0; bj < 2; ++bj) {
;             f32x2_t sc2[4], aux2[4];
; #pragma unroll
;             for (int j = 0; j < 4; ++j) {
;                 const float k0 = (KIND == 4) ? (0.125f * LOG2E / 127.0f) : (1.0f / 127.0f);
;                 sc2[j] = (f32x2_t){wmax[col0 + bj * HALF + 2 * j] * k0, wmax[col0 + bj * HALF + 2 * j + 1] * k0};
;                 if (KIND == 1) aux2[j] = (f32x2_t){lb[col0 - C_HG + bj * HALF + 2 * j], lb[col0 - C_HG + bj * HALF + 2 * j + 1]};
;                 else if (KIND == 3) aux2[j] = (f32x2_t){gain[col0 - C_HGATE + bj * HALF + 2 * j], gain[col0 - C_HGATE + bj * HALF + 2 * j + 1]};
;                 else aux2[j] = (f32x2_t){0.f, 0.f};
;             }
; #pragma unroll
;             for (int ai = 0; ai < 2; ++ai)
; #pragma unroll
;                 for (int m = 0; m < 4; ++m) { const int row = row0 + ai * HALF + m * 16; const float a = __shfl(ai ? sa_hi : sa_lo, 16 * m + fr);
;                     const f32x4 f0 = __builtin_convertvector(__builtin_bit_cast(i32x4, acc[ai][bj][m][0]), f32x4), f1 = __builtin_convertvector(__builtin_bit_cast(i32x4, acc[ai][bj][m][1]), f32x4);
;                     f32x2_t v[4] = {(f32x2_t){f0[0], f0[1]}, (f32x2_t){f0[2], f0[3]}, (f32x2_t){f1[0], f1[1]}, (f32x2_t){f1[2], f1[3]}};
; #pragma unroll
;                     for (int j = 0; j < 4; ++j) {
;                         v[j] = v[j] * (sc2[j] * (f32x2_t){a, a});
;                         if (KIND == 0 || KIND == 1 || KIND == 3) {
;                             const f32x2_t e = v[j] * (f32x2_t){-LOG2E, -LOG2E};
;                             const f32x2_t dn = (f32x2_t){__builtin_amdgcn_exp2f(e[0]), __builtin_amdgcn_exp2f(e[1])} + (f32x2_t){1.0f, 1.0f};
;                             const f32x2_t sg = (f32x2_t){fast_rcp(dn[0]), fast_rcp(dn[1])};
;                             if (KIND == 0) v[j] = v[j] * sg;
;                             else if (KIND == 3) v[j] = (v[j] * sg) * aux2[j];
.LBB0_222:
	s_andn2_b64 vcc, exec, s[8:9]
	v_lshlrev_b32_e32 v210, 2, v233
	v_lshlrev_b64 v[152:153], 1, v[146:147]
	v_or_b32_e32 v163, 16, v175
	v_or_b32_e32 v177, 32, v175
	v_or_b32_e32 v187, 48, v175
	v_add_u32_e32 v169, 0x80, v175
	v_add_u32_e32 v186, 0x90, v175
	v_add_u32_e32 v211, 0xa0, v175
	v_add_u32_e32 v234, 0xb0, v175
	s_cbranch_vccnz .LBB0_224
	global_load_dwordx2 v[150:151], v[148:149], off offset:24
	global_load_dwordx4 v[134:137], v[148:149], off offset:8
	global_load_dwordx4 v[236:239], v[148:149], off offset:528
	global_load_dwordx4 v[240:243], v[148:149], off offset:512
	s_waitcnt vmcnt(0)
	ds_bpermute_b32 v66, v210, v209
	s_mov_b32 s2, 0x3c010204
	v_cvt_f32_i32_e32 v157, v129
	v_cvt_f32_i32_e32 v156, v128
	v_pk_mul_f32 v[132:133], v[154:155], s[2:3] op_sel_hi:[1,0]
	v_cvt_f32_i32_e32 v161, v125
	v_cvt_f32_i32_e32 v160, v124
	v_cvt_f32_i32_e32 v159, v127
	v_cvt_f32_i32_e32 v158, v126
	s_waitcnt lgkmcnt(0)
	v_pk_mul_f32 v[164:165], v[132:133], v[66:67] op_sel_hi:[1,0]
	v_cvt_f32_i32_e32 v167, v119
	v_pk_mul_f32 v[156:157], v[156:157], v[164:165]
	v_cvt_f32_i32_e32 v166, v118
	v_cvt_pk_bf16_f32 v170, v156, v157
	ds_bpermute_b32 v156, v210, v209 offset:64
	ds_bpermute_b32 v162, v210, v209 offset:128
	ds_bpermute_b32 v168, v210, v209 offset:192
	v_cvt_f32_i32_e32 v183, v93
	v_cvt_f32_i32_e32 v182, v92
	v_cvt_f32_i32_e32 v189, v85
	s_waitcnt lgkmcnt(1)
	v_pk_mul_f32 v[178:179], v[132:133], v[162:163] op_sel_hi:[1,0]
	s_waitcnt lgkmcnt(0)
	v_pk_mul_f32 v[180:181], v[132:133], v[168:169] op_sel_hi:[1,0]
	v_cvt_f32_i32_e32 v188, v84
	ds_bpermute_b32 v174, v210, v208 offset:128
	ds_bpermute_b32 v176, v210, v208 offset:192
	s_waitcnt lgkmcnt(1)
	v_pk_mul_f32 v[192:193], v[132:133], v[174:175] op_sel_hi:[1,0]
	v_pk_mul_f32 v[138:139], v[134:135], s[2:3] op_sel_hi:[1,0]
	v_pk_mul_f32 v[134:135], v[150:151], s[2:3] op_sel_hi:[1,0]
	v_cvt_f32_i32_e32 v151, v131
	v_cvt_f32_i32_e32 v150, v130
	v_pk_mul_f32 v[136:137], v[136:137], s[2:3] op_sel_hi:[1,0]
	v_pk_mul_f32 v[164:165], v[138:139], v[66:67] op_sel_hi:[1,0]
	s_nop 0
	v_pk_mul_f32 v[150:151], v[150:151], v[164:165]
	v_pk_mul_f32 v[164:165], v[136:137], v[66:67] op_sel_hi:[1,0]
	v_cvt_pk_bf16_f32 v171, v150, v151
	v_pk_mul_f32 v[160:161], v[160:161], v[164:165]
	v_pk_mul_f32 v[164:165], v[134:135], v[66:67] op_sel_hi:[1,0]
	v_cvt_pk_bf16_f32 v172, v160, v161
	v_pk_mul_f32 v[158:159], v[158:159], v[164:165]
	v_mov_b64_e32 v[164:165], s[14:15]
	v_mad_i64_i32 v[150:151], s[0:1], v175, s81, v[164:165]
	v_cvt_f32_i32_e32 v161, v121
	v_cvt_f32_i32_e32 v160, v120
	v_cvt_pk_bf16_f32 v173, v158, v159
	v_lshl_add_u64 v[158:159], v[150:151], 0, v[152:153]
	v_cvt_f32_i32_e32 v151, v123
	v_cvt_f32_i32_e32 v150, v122
	global_store_dwordx4 v[158:159], v[170:173], off
	s_nop 1
	v_cvt_f32_i32_e32 v171, v117
	v_cvt_f32_i32_e32 v170, v116
	v_pk_mul_f32 v[172:173], v[132:133], v[156:157] op_sel_hi:[1,0]
	s_nop 0
	v_pk_mul_f32 v[160:161], v[160:161], v[172:173]
	v_pk_mul_f32 v[172:173], v[138:139], v[156:157] op_sel_hi:[1,0]
	s_nop 0
	v_pk_mul_f32 v[150:151], v[150:151], v[172:173]
	v_pk_mul_f32 v[172:173], v[136:137], v[156:157] op_sel_hi:[1,0]
	s_nop 0
	v_pk_mul_f32 v[172:173], v[170:171], v[172:173]
	v_pk_mul_f32 v[170:171], v[134:135], v[156:157] op_sel_hi:[1,0]
	v_cvt_pk_bf16_f32 v172, v172, v173
	v_pk_mul_f32 v[166:167], v[166:167], v[170:171]
	v_cvt_pk_bf16_f32 v171, v150, v151
	v_cvt_pk_bf16_f32 v173, v166, v167
	v_mad_i64_i32 v[150:151], s[0:1], v163, s81, v[164:165]
	v_cvt_f32_i32_e32 v167, v113
	v_cvt_f32_i32_e32 v166, v112
	v_cvt_pk_bf16_f32 v170, v160, v161
	v_lshl_add_u64 v[160:161], v[150:151], 0, v[152:153]
	v_cvt_f32_i32_e32 v151, v115
	v_cvt_f32_i32_e32 v150, v114
	global_store_dwordx4 v[160:161], v[170:173], off
	v_pk_mul_f32 v[166:167], v[166:167], v[178:179]
	v_pk_mul_f32 v[178:179], v[138:139], v[162:163] op_sel_hi:[1,0]
	v_cvt_f32_i32_e32 v173, v109
	v_cvt_f32_i32_e32 v172, v108
	v_cvt_f32_i32_e32 v171, v111
	v_cvt_f32_i32_e32 v170, v110
	v_pk_mul_f32 v[150:151], v[150:151], v[178:179]
	v_pk_mul_f32 v[178:179], v[136:137], v[162:163] op_sel_hi:[1,0]
	s_nop 0
	v_pk_mul_f32 v[172:173], v[172:173], v[178:179]
	v_pk_mul_f32 v[178:179], v[134:135], v[162:163] op_sel_hi:[1,0]
	v_cvt_pk_bf16_f32 v172, v172, v173
	v_pk_mul_f32 v[178:179], v[170:171], v[178:179]
	v_cvt_pk_bf16_f32 v171, v150, v151
	v_mad_i64_i32 v[150:151], s[0:1], v177, s81, v[164:165]
	v_cvt_pk_bf16_f32 v170, v166, v167
	v_cvt_pk_bf16_f32 v173, v178, v179
	v_lshl_add_u64 v[166:167], v[150:151], 0, v[152:153]
	global_store_dwordx4 v[166:167], v[170:173], off
	v_cvt_f32_i32_e32 v151, v107
	v_cvt_f32_i32_e32 v150, v106
	v_cvt_f32_i32_e32 v171, v105
	v_cvt_f32_i32_e32 v170, v104
	v_cvt_f32_i32_e32 v179, v101
	v_cvt_f32_i32_e32 v178, v100
	v_cvt_f32_i32_e32 v173, v103
	v_cvt_f32_i32_e32 v172, v102
	v_pk_mul_f32 v[170:171], v[170:171], v[180:181]
	v_pk_mul_f32 v[180:181], v[138:139], v[168:169] op_sel_hi:[1,0]
	v_cvt_pk_bf16_f32 v170, v170, v171
	v_pk_mul_f32 v[150:151], v[150:151], v[180:181]
	v_pk_mul_f32 v[180:181], v[136:137], v[168:169] op_sel_hi:[1,0]
	v_cvt_pk_bf16_f32 v171, v150, v151
	v_pk_mul_f32 v[178:179], v[178:179], v[180:181]
	v_pk_mul_f32 v[180:181], v[134:135], v[168:169] op_sel_hi:[1,0]
	v_mad_i64_i32 v[150:151], s[0:1], v187, s81, v[164:165]
	v_pk_mul_f32 v[180:181], v[172:173], v[180:181]
	v_cvt_pk_bf16_f32 v172, v178, v179
	v_cvt_pk_bf16_f32 v173, v180, v181
	v_lshl_add_u64 v[178:179], v[150:151], 0, v[152:153]
	global_store_dwordx4 v[178:179], v[170:173], off
	ds_bpermute_b32 v170, v210, v208
	v_cvt_f32_i32_e32 v151, v99
	v_cvt_f32_i32_e32 v173, v97
	v_cvt_f32_i32_e32 v172, v96
	v_cvt_f32_i32_e32 v150, v98
	v_cvt_f32_i32_e32 v181, v95
	v_cvt_f32_i32_e32 v180, v94
	s_waitcnt lgkmcnt(0)
;     template <int KIND>
;     __device__ __forceinline__ void run(const f32x4 (&acc)[2][2][4][2], const Unit& u, int wr, int wc, int fr, int fq) const {
;         const int row0 = u.pm * BM + wr * 64 + fr, col0 = u.pn * BM + wc * 32 + 8 * fq;
;         const float sa_lo = sa[u.pm * BM + wr * 64 + fr + 16 * fq], sa_hi = sa[u.pm * BM + HALF + wr * 64 + fr + 16 * fq];
; #pragma unroll
;         for (int bj = 0; bj < 2; ++bj) {
;             f32x2_t sc2[4], aux2[4];
; #pragma unroll
;             for (int j = 0; j < 4; ++j) {
;                 const float k0 = (KIND == 4) ? (0.125f * LOG2E / 127.0f) : (1.0f / 127.0f);
;                 sc2[j] = (f32x2_t){wmax[col0 + bj * HALF + 2 * j] * k0, wmax[col0 + bj * HALF + 2 * j + 1] * k0};
;                 if (KIND == 1) aux2[j] = (f32x2_t){lb[col0 - C_HG + bj * HALF + 2 * j], lb[col0 - C_HG + bj * HALF + 2 * j + 1]};
;                 else if (KIND == 3) aux2[j] = (f32x2_t){gain[col0 - C_HGATE + bj * HALF + 2 * j], gain[col0 - C_HGATE + bj * HALF + 2 * j + 1]};
;                 else aux2[j] = (f32x2_t){0.f, 0.f};
;             }
; #pragma unroll
;             for (int ai = 0; ai < 2; ++ai)
; #pragma unroll
;                 for (int m = 0; m < 4; ++m) { const int row = row0 + ai * HALF + m * 16; const float a = __shfl(ai ? sa_hi : sa_lo, 16 * m + fr);
;                     const f32x4 f0 = __builtin_convertvector(__builtin_bit_cast(i32x4, acc[ai][bj][m][0]), f32x4), f1 = __builtin_convertvector(__builtin_bit_cast(i32x4, acc[ai][bj][m][1]), f32x4);
;                     f32x2_t v[4] = {(f32x2_t){f0[0], f0[1]}, (f32x2_t){f0[2], f0[3]}, (f32x2_t){f1[0], f1[1]}, (f32x2_t){f1[2], f1[3]}};
; #pragma unroll
;                     for (int j = 0; j < 4; ++j) {
;                         v[j] = v[j] * (sc2[j] * (f32x2_t){a, a});
;                         if (KIND == 0 || KIND == 1 || KIND == 3) {
;                             const f32x2_t e = v[j] * (f32x2_t){-LOG2E, -LOG2E};
;                             const f32x2_t dn = (f32x2_t){__builtin_amdgcn_exp2f(e[0]), __builtin_amdgcn_exp2f(e[1])} + (f32x2_t){1.0f, 1.0f};
;                             const f32x2_t sg = (f32x2_t){fast_rcp(dn[0]), fast_rcp(dn[1])};
;                             if (KIND == 0) v[j] = v[j] * sg;
;                             else if (KIND == 3) v[j] = (v[j] * sg) * aux2[j];
	v_pk_mul_f32 v[184:185], v[132:133], v[170:171] op_sel_hi:[1,0]
	s_nop 0
	v_pk_mul_f32 v[172:173], v[172:173], v[184:185]
	v_pk_mul_f32 v[184:185], v[138:139], v[170:171] op_sel_hi:[1,0]
	s_nop 0
	v_pk_mul_f32 v[150:151], v[150:151], v[184:185]
	v_pk_mul_f32 v[184:185], v[136:137], v[170:171] op_sel_hi:[1,0]
	s_nop 0
	v_pk_mul_f32 v[184:185], v[182:183], v[184:185]
	v_pk_mul_f32 v[182:183], v[134:135], v[170:171] op_sel_hi:[1,0]
	v_cvt_pk_bf16_f32 v184, v184, v185
	v_pk_mul_f32 v[180:181], v[180:181], v[182:183]
	v_cvt_pk_bf16_f32 v182, v172, v173
	v_cvt_pk_bf16_f32 v183, v150, v151
	v_mad_i64_i32 v[150:151], s[0:1], v169, s81, v[164:165]
	ds_bpermute_b32 v172, v210, v208 offset:64
	v_cvt_pk_bf16_f32 v185, v180, v181
	v_lshl_add_u64 v[180:181], v[150:151], 0, v[152:153]
	global_store_dwordx4 v[180:181], v[182:185], off
	v_cvt_f32_i32_e32 v151, v91
	v_cvt_f32_i32_e32 v150, v90
	v_cvt_f32_i32_e32 v183, v89
	v_cvt_f32_i32_e32 v182, v88
	v_cvt_f32_i32_e32 v185, v87
	v_cvt_f32_i32_e32 v184, v86
	s_waitcnt lgkmcnt(0)
	v_pk_mul_f32 v[190:191], v[132:133], v[172:173] op_sel_hi:[1,0]
	v_pk_mul_f32 v[132:133], v[132:133], v[176:177] op_sel_hi:[1,0]
	v_pk_mul_f32 v[182:183], v[182:183], v[190:191]
	v_pk_mul_f32 v[190:191], v[138:139], v[172:173] op_sel_hi:[1,0]
	s_nop 0
	v_pk_mul_f32 v[150:151], v[150:151], v[190:191]
	v_pk_mul_f32 v[190:191], v[136:137], v[172:173] op_sel_hi:[1,0]
	s_nop 0
	v_pk_mul_f32 v[190:191], v[188:189], v[190:191]
	v_pk_mul_f32 v[188:189], v[134:135], v[172:173] op_sel_hi:[1,0]
	v_cvt_pk_bf16_f32 v190, v190, v191
	v_pk_mul_f32 v[184:185], v[184:185], v[188:189]
	v_cvt_pk_bf16_f32 v189, v150, v151
	v_cvt_pk_bf16_f32 v191, v184, v185
	v_mad_i64_i32 v[150:151], s[0:1], v186, s81, v[164:165]
	v_cvt_f32_i32_e32 v185, v81
	v_cvt_f32_i32_e32 v184, v80
	v_cvt_pk_bf16_f32 v188, v182, v183
	v_lshl_add_u64 v[182:183], v[150:151], 0, v[152:153]
	v_cvt_f32_i32_e32 v151, v83
	v_cvt_f32_i32_e32 v150, v82
	global_store_dwordx4 v[182:183], v[188:191], off
	v_pk_mul_f32 v[184:185], v[184:185], v[192:193]
	v_pk_mul_f32 v[192:193], v[138:139], v[174:175] op_sel_hi:[1,0]
	v_cvt_f32_i32_e32 v191, v77
	v_cvt_f32_i32_e32 v190, v76
	v_cvt_f32_i32_e32 v189, v79
	v_cvt_f32_i32_e32 v188, v78
	v_pk_mul_f32 v[150:151], v[150:151], v[192:193]
	v_pk_mul_f32 v[192:193], v[136:137], v[174:175] op_sel_hi:[1,0]
	v_pk_mul_f32 v[136:137], v[136:137], v[176:177] op_sel_hi:[1,0]
	v_pk_mul_f32 v[190:191], v[190:191], v[192:193]
	v_pk_mul_f32 v[192:193], v[134:135], v[174:175] op_sel_hi:[1,0]
	v_cvt_pk_bf16_f32 v190, v190, v191
	v_pk_mul_f32 v[192:193], v[188:189], v[192:193]
	v_cvt_pk_bf16_f32 v189, v150, v151
	v_mad_i64_i32 v[150:151], s[0:1], v211, s81, v[164:165]
	v_cvt_pk_bf16_f32 v188, v184, v185
	v_cvt_pk_bf16_f32 v191, v192, v193
	v_lshl_add_u64 v[184:185], v[150:151], 0, v[152:153]
	v_cvt_f32_i32_e32 v193, v69
	v_cvt_f32_i32_e32 v192, v68
	global_store_dwordx4 v[184:185], v[188:191], off
	v_cvt_f32_i32_e32 v151, v75
	v_cvt_f32_i32_e32 v150, v74
	v_cvt_f32_i32_e32 v189, v73
	v_cvt_f32_i32_e32 v188, v72
	v_cvt_f32_i32_e32 v191, v71
	v_cvt_f32_i32_e32 v190, v70
	v_pk_mul_f32 v[138:139], v[138:139], v[176:177] op_sel_hi:[1,0]
	v_pk_mul_f32 v[136:137], v[192:193], v[136:137]
	v_pk_mul_f32 v[134:135], v[134:135], v[176:177] op_sel_hi:[1,0]
	v_pk_mul_f32 v[132:133], v[188:189], v[132:133]
	v_pk_mul_f32 v[138:139], v[150:151], v[138:139]
	v_pk_mul_f32 v[150:151], v[190:191], v[134:135]
	v_cvt_pk_bf16_f32 v134, v136, v137
	v_mad_i64_i32 v[136:137], s[0:1], v234, s81, v[164:165]
	v_cvt_pk_bf16_f32 v132, v132, v133
	v_cvt_pk_bf16_f32 v133, v138, v139
	v_cvt_pk_bf16_f32 v135, v150, v151
	v_lshl_add_u64 v[136:137], v[136:137], 0, v[152:153]
	global_store_dwordx4 v[136:137], v[132:135], off
	s_nop 1
	v_mov_b32_e32 v132, v236
	v_mov_b32_e32 v133, v237
	v_mov_b32_e32 v134, v238
	v_mov_b32_e32 v135, v239
	v_mov_b32_e32 v136, v240
	v_mov_b32_e32 v137, v241
	v_mov_b32_e32 v138, v242
	v_mov_b32_e32 v139, v243
	v_cvt_f32_i32_e32 v193, v59
	v_cvt_f32_i32_e32 v192, v58
	v_cvt_f32_i32_e32 v191, v61
	v_cvt_f32_i32_e32 v190, v60
	v_mad_i64_i32 v[150:151], s[0:1], v234, s81, 0
	s_mov_b64 s[0:1], 0
	v_pk_mul_f32 v[132:133], v[132:133], s[2:3] op_sel_hi:[1,0]
	v_pk_mul_f32 v[188:189], v[138:139], s[2:3] op_sel_hi:[1,0]
	v_cvt_f32_i32_e32 v139, v63
	v_cvt_f32_i32_e32 v138, v62
	v_pk_mul_f32 v[164:165], v[136:137], s[2:3] op_sel_hi:[1,0]
	v_cvt_f32_i32_e32 v137, v65
	v_cvt_f32_i32_e32 v136, v64
	v_pk_mul_f32 v[194:195], v[66:67], v[164:165] op_sel_hi:[0,1]
	v_pk_mul_f32 v[138:139], v[138:139], v[194:195]
	v_pk_mul_f32 v[194:195], v[66:67], v[188:189] op_sel_hi:[0,1]
	v_pk_mul_f32 v[134:135], v[134:135], s[2:3] op_sel_hi:[1,0]
	v_pk_mul_f32 v[194:195], v[136:137], v[194:195]
	v_pk_mul_f32 v[136:137], v[66:67], v[132:133] op_sel_hi:[0,1]
	v_pk_mul_f32 v[192:193], v[192:193], v[136:137]
	v_pk_mul_f32 v[136:137], v[66:67], v[134:135] op_sel_hi:[0,1]
	v_pk_mul_f32 v[190:191], v[190:191], v[136:137]
	v_cvt_pk_bf16_f32 v136, v138, v139
	v_cvt_pk_bf16_f32 v137, v194, v195
	v_cvt_pk_bf16_f32 v138, v192, v193
	v_cvt_pk_bf16_f32 v139, v190, v191
	global_store_dwordx4 v[158:159], v[136:139], off offset:256
	v_cvt_f32_i32_e32 v191, v51
	v_cvt_f32_i32_e32 v190, v50
	v_cvt_f32_i32_e32 v139, v55
	v_cvt_f32_i32_e32 v138, v54
	v_cvt_f32_i32_e32 v137, v57
	v_cvt_f32_i32_e32 v136, v56
	v_cvt_f32_i32_e32 v159, v53
	v_cvt_f32_i32_e32 v158, v52
	v_pk_mul_f32 v[192:193], v[156:157], v[164:165] op_sel_hi:[0,1]
	v_pk_mul_f32 v[138:139], v[138:139], v[192:193]
	v_pk_mul_f32 v[192:193], v[156:157], v[188:189] op_sel_hi:[0,1]
	v_pk_mul_f32 v[192:193], v[136:137], v[192:193]
;     template <int KIND>
;     __device__ __forceinline__ void run(const f32x4 (&acc)[2][2][4][2], const Unit& u, int wr, int wc, int fr, int fq) const {
;         const int row0 = u.pm * BM + wr * 64 + fr, col0 = u.pn * BM + wc * 32 + 8 * fq;
;         const float sa_lo = sa[u.pm * BM + wr * 64 + fr + 16 * fq], sa_hi = sa[u.pm * BM + HALF + wr * 64 + fr + 16 * fq];
; #pragma unroll
;         for (int bj = 0; bj < 2; ++bj) {
;             f32x2_t sc2[4], aux2[4];
; #pragma unroll
;             for (int j = 0; j < 4; ++j) {
;                 const float k0 = (KIND == 4) ? (0.125f * LOG2E / 127.0f) : (1.0f / 127.0f);
;                 sc2[j] = (f32x2_t){wmax[col0 + bj * HALF + 2 * j] * k0, wmax[col0 + bj * HALF + 2 * j + 1] * k0};
;                 if (KIND == 1) aux2[j] = (f32x2_t){lb[col0 - C_HG + bj * HALF + 2 * j], lb[col0 - C_HG + bj * HALF + 2 * j + 1]};
;                 else if (KIND == 3) aux2[j] = (f32x2_t){gain[col0 - C_HGATE + bj * HALF + 2 * j], gain[col0 - C_HGATE + bj * HALF + 2 * j + 1]};
;                 else aux2[j] = (f32x2_t){0.f, 0.f};
;             }
; #pragma unroll
;             for (int ai = 0; ai < 2; ++ai)
; #pragma unroll
;                 for (int m = 0; m < 4; ++m) { const int row = row0 + ai * HALF + m * 16; const float a = __shfl(ai ? sa_hi : sa_lo, 16 * m + fr);
;                     const f32x4 f0 = __builtin_convertvector(__builtin_bit_cast(i32x4, acc[ai][bj][m][0]), f32x4), f1 = __builtin_convertvector(__builtin_bit_cast(i32x4, acc[ai][bj][m][1]), f32x4);
;                     f32x2_t v[4] = {(f32x2_t){f0[0], f0[1]}, (f32x2_t){f0[2], f0[3]}, (f32x2_t){f1[0], f1[1]}, (f32x2_t){f1[2], f1[3]}};
; #pragma unroll
;                     for (int j = 0; j < 4; ++j) {
;                         v[j] = v[j] * (sc2[j] * (f32x2_t){a, a});
;                         if (KIND == 0 || KIND == 1 || KIND == 3) {
;                             const f32x2_t e = v[j] * (f32x2_t){-LOG2E, -LOG2E};
;                             const f32x2_t dn = (f32x2_t){__builtin_amdgcn_exp2f(e[0]), __builtin_amdgcn_exp2f(e[1])} + (f32x2_t){1.0f, 1.0f};
;                             const f32x2_t sg = (f32x2_t){fast_rcp(dn[0]), fast_rcp(dn[1])};
;                             if (KIND == 0) v[j] = v[j] * sg;
;                             else if (KIND == 3) v[j] = (v[j] * sg) * aux2[j];
	v_pk_mul_f32 v[136:137], v[156:157], v[132:133] op_sel_hi:[0,1]
	v_pk_mul_f32 v[190:191], v[190:191], v[136:137]
	v_pk_mul_f32 v[136:137], v[156:157], v[134:135] op_sel_hi:[0,1]
	v_pk_mul_f32 v[156:157], v[158:159], v[136:137]
	v_cvt_pk_bf16_f32 v136, v138, v139
	v_cvt_pk_bf16_f32 v137, v192, v193
	v_cvt_pk_bf16_f32 v138, v190, v191
	v_cvt_pk_bf16_f32 v139, v156, v157
	global_store_dwordx4 v[160:161], v[136:139], off offset:256
	v_cvt_f32_i32_e32 v159, v43
	v_cvt_f32_i32_e32 v158, v42
	v_cvt_f32_i32_e32 v139, v47
	v_cvt_f32_i32_e32 v138, v46
	v_cvt_f32_i32_e32 v137, v49
	v_cvt_f32_i32_e32 v136, v48
	v_cvt_f32_i32_e32 v157, v45
	v_cvt_f32_i32_e32 v156, v44
	v_pk_mul_f32 v[160:161], v[162:163], v[164:165] op_sel_hi:[0,1]
	v_pk_mul_f32 v[138:139], v[138:139], v[160:161]
	v_pk_mul_f32 v[160:161], v[162:163], v[188:189] op_sel_hi:[0,1]
	v_pk_mul_f32 v[160:161], v[136:137], v[160:161]
	v_pk_mul_f32 v[136:137], v[162:163], v[132:133] op_sel_hi:[0,1]
	v_pk_mul_f32 v[158:159], v[158:159], v[136:137]
	v_pk_mul_f32 v[136:137], v[162:163], v[134:135] op_sel_hi:[0,1]
	v_pk_mul_f32 v[156:157], v[156:157], v[136:137]
	v_cvt_pk_bf16_f32 v136, v138, v139
	v_cvt_pk_bf16_f32 v137, v160, v161
	v_cvt_pk_bf16_f32 v138, v158, v159
	v_cvt_pk_bf16_f32 v139, v156, v157
	global_store_dwordx4 v[166:167], v[136:139], off offset:256
	v_cvt_f32_i32_e32 v159, v35
	v_cvt_f32_i32_e32 v158, v34
	v_cvt_f32_i32_e32 v139, v39
	v_cvt_f32_i32_e32 v138, v38
	v_cvt_f32_i32_e32 v137, v41
	v_cvt_f32_i32_e32 v136, v40
	v_cvt_f32_i32_e32 v157, v37
	v_cvt_f32_i32_e32 v156, v36
	v_pk_mul_f32 v[160:161], v[168:169], v[164:165] op_sel_hi:[0,1]
	v_pk_mul_f32 v[138:139], v[138:139], v[160:161]
	v_pk_mul_f32 v[160:161], v[168:169], v[188:189] op_sel_hi:[0,1]
	v_pk_mul_f32 v[160:161], v[136:137], v[160:161]
	v_pk_mul_f32 v[136:137], v[168:169], v[132:133] op_sel_hi:[0,1]
	v_pk_mul_f32 v[158:159], v[158:159], v[136:137]
	v_pk_mul_f32 v[136:137], v[168:169], v[134:135] op_sel_hi:[0,1]
	v_pk_mul_f32 v[156:157], v[156:157], v[136:137]
	v_cvt_pk_bf16_f32 v136, v138, v139
	v_cvt_pk_bf16_f32 v137, v160, v161
	v_cvt_pk_bf16_f32 v138, v158, v159
	v_cvt_pk_bf16_f32 v139, v156, v157
	global_store_dwordx4 v[178:179], v[136:139], off offset:256
	v_cvt_f32_i32_e32 v159, v27
	v_cvt_f32_i32_e32 v158, v26
	v_cvt_f32_i32_e32 v139, v31
	v_cvt_f32_i32_e32 v138, v30
	v_cvt_f32_i32_e32 v137, v33
	v_cvt_f32_i32_e32 v136, v32
	v_cvt_f32_i32_e32 v157, v29
	v_cvt_f32_i32_e32 v156, v28
	v_pk_mul_f32 v[160:161], v[170:171], v[164:165] op_sel_hi:[0,1]
	v_pk_mul_f32 v[138:139], v[138:139], v[160:161]
	v_pk_mul_f32 v[160:161], v[170:171], v[188:189] op_sel_hi:[0,1]
	v_pk_mul_f32 v[160:161], v[136:137], v[160:161]
	v_pk_mul_f32 v[136:137], v[170:171], v[132:133] op_sel_hi:[0,1]
	v_pk_mul_f32 v[158:159], v[158:159], v[136:137]
	v_pk_mul_f32 v[136:137], v[170:171], v[134:135] op_sel_hi:[0,1]
	v_pk_mul_f32 v[156:157], v[156:157], v[136:137]
	v_cvt_pk_bf16_f32 v136, v138, v139
	v_cvt_pk_bf16_f32 v137, v160, v161
	v_cvt_pk_bf16_f32 v138, v158, v159
	v_cvt_pk_bf16_f32 v139, v156, v157
	global_store_dwordx4 v[180:181], v[136:139], off offset:256
	v_cvt_f32_i32_e32 v159, v19
	v_cvt_f32_i32_e32 v158, v18
	v_cvt_f32_i32_e32 v139, v23
	v_cvt_f32_i32_e32 v138, v22
	v_cvt_f32_i32_e32 v137, v25
	v_cvt_f32_i32_e32 v136, v24
	v_cvt_f32_i32_e32 v157, v21
	v_cvt_f32_i32_e32 v156, v20
	v_pk_mul_f32 v[160:161], v[172:173], v[164:165] op_sel_hi:[0,1]
	v_pk_mul_f32 v[138:139], v[138:139], v[160:161]
	v_pk_mul_f32 v[160:161], v[172:173], v[188:189] op_sel_hi:[0,1]
	v_pk_mul_f32 v[160:161], v[136:137], v[160:161]
	v_pk_mul_f32 v[136:137], v[172:173], v[132:133] op_sel_hi:[0,1]
	v_pk_mul_f32 v[158:159], v[158:159], v[136:137]
	v_pk_mul_f32 v[136:137], v[172:173], v[134:135] op_sel_hi:[0,1]
	v_pk_mul_f32 v[156:157], v[156:157], v[136:137]
	v_cvt_pk_bf16_f32 v136, v138, v139
	v_cvt_pk_bf16_f32 v137, v160, v161
	v_cvt_pk_bf16_f32 v138, v158, v159
	v_cvt_pk_bf16_f32 v139, v156, v157
	global_store_dwordx4 v[182:183], v[136:139], off offset:256
	v_cvt_f32_i32_e32 v159, v11
	v_cvt_f32_i32_e32 v158, v10
	v_cvt_f32_i32_e32 v139, v15
	v_cvt_f32_i32_e32 v138, v14
	v_cvt_f32_i32_e32 v137, v17
	v_cvt_f32_i32_e32 v136, v16
	v_cvt_f32_i32_e32 v157, v13
	v_cvt_f32_i32_e32 v156, v12
	v_pk_mul_f32 v[160:161], v[174:175], v[164:165] op_sel_hi:[0,1]
	v_pk_mul_f32 v[138:139], v[138:139], v[160:161]
	v_pk_mul_f32 v[160:161], v[174:175], v[188:189] op_sel_hi:[0,1]
	v_pk_mul_f32 v[160:161], v[136:137], v[160:161]
	v_pk_mul_f32 v[136:137], v[174:175], v[132:133] op_sel_hi:[0,1]
	v_pk_mul_f32 v[158:159], v[158:159], v[136:137]
	v_pk_mul_f32 v[136:137], v[174:175], v[134:135] op_sel_hi:[0,1]
	v_pk_mul_f32 v[156:157], v[156:157], v[136:137]
	v_cvt_pk_bf16_f32 v136, v138, v139
	v_cvt_pk_bf16_f32 v137, v160, v161
	v_cvt_pk_bf16_f32 v138, v158, v159
	v_cvt_pk_bf16_f32 v139, v156, v157
	global_store_dwordx4 v[184:185], v[136:139], off offset:256
	v_cvt_f32_i32_e32 v157, v5
	v_cvt_f32_i32_e32 v156, v4
	v_cvt_f32_i32_e32 v137, v7
	v_cvt_f32_i32_e32 v136, v6
	v_cvt_f32_i32_e32 v139, v9
	v_cvt_f32_i32_e32 v138, v8
	v_cvt_f32_i32_e32 v159, v3
	v_cvt_f32_i32_e32 v158, v2
	v_pk_mul_f32 v[160:161], v[176:177], v[164:165] op_sel_hi:[0,1]
	v_pk_mul_f32 v[136:137], v[136:137], v[160:161]
	v_pk_mul_f32 v[160:161], v[176:177], v[188:189] op_sel_hi:[0,1]
	v_pk_mul_f32 v[132:133], v[176:177], v[132:133] op_sel_hi:[0,1]
	v_pk_mul_f32 v[134:135], v[176:177], v[134:135] op_sel_hi:[0,1]
	v_pk_mul_f32 v[138:139], v[138:139], v[160:161]
	v_pk_mul_f32 v[132:133], v[158:159], v[132:133]
	v_pk_mul_f32 v[134:135], v[156:157], v[134:135]
